# out-proj epilogue rewritten by hand (row-folded full-line loads/stores, prefetched residual); 16 copy workers during out-proj
# speedup vs baseline: 1.0184x; 1.0184x over previous
.LBB0_1105:
	s_load_dword s3, s[0:1], 0xa8
	s_mov_b64 s[4:5], -1
	s_waitcnt lgkmcnt(0)
	s_addk_i32 s3, 0xffb0
	s_cmp_lt_i32 s2, s3
	s_cbranch_scc1 .LBB0_1127
	s_cmpk_lt_i32 s2, 0xf0
	s_cbranch_scc1 .LBB0_1126
	s_load_dwordx4 s[12:15], s[0:1], 0x90
	s_cmp_eq_u32 s3, 0
	s_cselect_b64 s[10:11], -1, 0
	s_cmp_lg_u32 s3, 0
	s_cselect_b64 s[8:9], -1, 0
	s_waitcnt lgkmcnt(0)
	s_add_u32 s18, s14, 0x6330c88
	s_addc_u32 s19, s15, 0
	s_add_u32 s14, s14, 0x6330c80
	s_waitcnt vmcnt(0)
	v_or_b32_e32 v0, 0x400, v156
	s_addc_u32 s15, s15, 0
	v_or_b32_e32 v2, 0x800, v156
	v_or_b32_e32 v4, 0xc00, v156
	v_or_b32_e32 v6, 0x1000, v156
	v_or_b32_e32 v8, 0x1400, v156
	v_or_b32_e32 v10, 0x1800, v156
	v_or_b32_e32 v12, 0x1c00, v156
	v_or_b32_e32 v14, 0x2000, v156
	v_or_b32_e32 v16, 0x2400, v156
	v_or_b32_e32 v18, 0x2800, v156
	v_or_b32_e32 v20, 0x2c00, v156
	v_or_b32_e32 v22, 0x3000, v156
	v_or_b32_e32 v24, 0x3400, v156
	v_or_b32_e32 v26, 0x3800, v156
	v_or_b32_e32 v28, 0x3c00, v156
	v_or_b32_e32 v30, 0x4000, v156
	v_or_b32_e32 v32, 0x4400, v156
	v_or_b32_e32 v34, 0x4800, v156
	v_or_b32_e32 v36, 0x4c00, v156
	v_or_b32_e32 v38, 0x5000, v156
	v_or_b32_e32 v40, 0x5400, v156
	v_or_b32_e32 v42, 0x5800, v156
	v_or_b32_e32 v146, 0x7c00, v156
	s_movk_i32 s4, 0x7fc0
	s_movk_i32 s6, 0x1c0
	s_add_i32 s28, 0, 0x252f0
	v_lshlrev_b32_e32 v131, 4, v0
	v_cndmask_b32_e64 v0, 0, 1, s[8:9]
	v_mov_b32_e32 v129, 0
	s_movk_i32 s26, 0x2000
	v_or_b32_e32 v130, 0x5c00, v156
	s_movk_i32 s27, 0x6000
	v_or_b32_e32 v132, 0x6000, v156
	v_or_b32_e32 v134, 0x6400, v156
	v_or_b32_e32 v136, 0x6800, v156
	v_or_b32_e32 v138, 0x6c00, v156
	v_or_b32_e32 v140, 0x7000, v156
	v_or_b32_e32 v142, 0x7400, v156
	v_or_b32_e32 v144, 0x7800, v156
	v_cmp_gt_u32_e64 s[4:5], s4, v146
	v_cmp_gt_u32_e64 s[6:7], s6, v156
	s_movk_i32 s29, 0x3ff
	s_mov_b32 s30, 0xb300000
	v_lshlrev_b32_e32 v128, 4, v156
	v_lshlrev_b32_e32 v133, 4, v2
	s_mov_b32 s31, 0xa000
	v_lshlrev_b32_e32 v135, 4, v4
	s_mov_b32 s33, 0xe000
	v_lshlrev_b32_e32 v137, 4, v6
	s_mov_b32 s34, 0x12000
	v_lshlrev_b32_e32 v139, 4, v8
	s_mov_b32 s35, 0x16000
	v_lshlrev_b32_e32 v141, 4, v10
	s_mov_b32 s38, 0x1a000
	v_lshlrev_b32_e32 v143, 4, v12
	s_mov_b32 s39, 0x1e000
	v_lshlrev_b32_e32 v145, 4, v14
	s_mov_b32 s44, 0x22000
	v_lshlrev_b32_e32 v147, 4, v16
	s_mov_b32 s45, 0x26000
	v_lshlrev_b32_e32 v152, 4, v18
	s_mov_b32 s46, 0x2a000
	v_lshlrev_b32_e32 v153, 4, v20
	s_mov_b32 s47, 0x2e000
	v_lshlrev_b32_e32 v154, 4, v22
	s_mov_b32 s48, 0x32000
	v_lshlrev_b32_e32 v155, 4, v24
	s_mov_b32 s49, 0x36000
	v_lshlrev_b32_e32 v157, 4, v26
	s_mov_b32 s50, 0x3a000
	v_lshlrev_b32_e32 v158, 4, v28
	s_mov_b32 s51, 0x3e000
	s_mov_b32 s52, 0x42000
	s_mov_b32 s53, 0x46000
	s_mov_b32 s54, 0x4a000
	s_mov_b32 s55, 0x4e000
	s_mov_b32 s56, 0x52000
	s_mov_b32 s57, 0x56000
	s_mov_b32 s58, 0x5a000
	s_mov_b32 s59, 0x5e000
	s_mov_b32 s60, 0x62000
	s_mov_b32 s61, 0x66000
	s_mov_b32 s62, 0x6a000
	s_mov_b32 s63, 0x6e000
	s_mov_b32 s64, 0x72000
	v_cmp_ne_u32_e64 s[8:9], 1, v0
	v_mov_b32_e32 v159, s28
	v_lshlrev_b32_e32 v160, 4, v30
	v_lshlrev_b32_e32 v161, 4, v32
	v_lshlrev_b32_e32 v162, 4, v34
	v_lshlrev_b32_e32 v163, 4, v36
	v_lshlrev_b32_e32 v164, 4, v38
	v_lshlrev_b32_e32 v165, 4, v40
	v_lshlrev_b32_e32 v166, 4, v42
	s_branch .LBB0_1109

.LBB0_1153:
	ds_read_b128 v[146:149], v153
	ds_read_b128 v[158:161], v153 offset:1024
	ds_read_b128 v[162:165], v153 offset:2048
	ds_read_b128 v[166:169], v153 offset:3072
	s_add_u32 s54, s52, 0xfff80080
	s_addc_u32 s55, s53, -1
	s_cmp_eq_u32 s80, 28
	s_cselect_b32 s55, s45, s55
	s_cselect_b32 s54, s51, s54
	s_cselect_b32 s83, s76, s79
	s_cselect_b32 s82, s77, s78
	v_lshl_add_u64 v[202:203], s[52:53], 0, v[136:137]
	s_add_i32 m0, s61, 0xc000
	ds_read_b128 v[170:173], v154
	ds_read_b128 v[174:177], v154 offset:1024
	ds_read_b128 v[178:181], v154 offset:2048
	ds_read_b128 v[182:185], v154 offset:3072
	ds_read_b128 v[186:189], v154 offset:4096
	ds_read_b128 v[190:193], v154 offset:5120
	ds_read_b128 v[194:197], v154 offset:6144
	ds_read_b128 v[198:201], v154 offset:7168
	global_load_lds_dwordx4 v[202:203], off
	v_lshl_add_u64 v[202:203], s[52:53], 0, v[138:139]
	s_add_i32 m0, s61, 0xe000
	s_nop 0
	global_load_lds_dwordx4 v[202:203], off
	s_waitcnt lgkmcnt(8)
	s_barrier
	s_waitcnt lgkmcnt(0)
	s_setprio 1
	s_waitcnt lgkmcnt(0)
	v_mfma_f32_16x16x32_bf16 v[124:127], v[146:149], v[170:173], v[124:127]
	v_mfma_f32_16x16x32_bf16 v[120:123], v[162:165], v[170:173], v[120:123]
	v_mfma_f32_16x16x32_bf16 v[108:111], v[146:149], v[178:181], v[108:111]
	v_mfma_f32_16x16x32_bf16 v[104:107], v[162:165], v[178:181], v[104:107]
	v_mfma_f32_16x16x32_bf16 v[92:95], v[146:149], v[186:189], v[92:95]
	v_mfma_f32_16x16x32_bf16 v[88:91], v[162:165], v[186:189], v[88:91]
	v_mfma_f32_16x16x32_bf16 v[76:79], v[146:149], v[194:197], v[76:79]
	v_mfma_f32_16x16x32_bf16 v[72:75], v[162:165], v[194:197], v[72:75]
	v_mfma_f32_16x16x32_bf16 v[124:127], v[158:161], v[174:177], v[124:127]
	v_mfma_f32_16x16x32_bf16 v[120:123], v[166:169], v[174:177], v[120:123]
	v_mfma_f32_16x16x32_bf16 v[108:111], v[158:161], v[182:185], v[108:111]
	v_mfma_f32_16x16x32_bf16 v[104:107], v[166:169], v[182:185], v[104:107]
	v_mfma_f32_16x16x32_bf16 v[92:95], v[158:161], v[190:193], v[92:95]
	v_mfma_f32_16x16x32_bf16 v[88:91], v[166:169], v[190:193], v[88:91]
	v_mfma_f32_16x16x32_bf16 v[76:79], v[158:161], v[198:201], v[76:79]
	v_mfma_f32_16x16x32_bf16 v[72:75], v[166:169], v[198:201], v[72:75]
	s_setprio 0
	s_barrier
	s_add_i32 s81, s70, s60
	v_lshl_add_u64 v[218:219], s[82:83], 0, v[128:129]
	s_mov_b32 m0, s81
	ds_read_b128 v[202:205], v155
	ds_read_b128 v[206:209], v155 offset:1024
	ds_read_b128 v[210:213], v155 offset:2048
	ds_read_b128 v[214:217], v155 offset:3072
	global_load_lds_dwordx4 v[218:219], off
	v_lshl_add_u64 v[220:221], v[218:219], 0, s[12:13]
	s_add_i32 m0, s81, 0x2000
	s_nop 0
	global_load_lds_dwordx4 v[220:221], off
	s_barrier
	s_waitcnt lgkmcnt(0)
	s_setprio 1
	s_waitcnt lgkmcnt(0)
	v_mfma_f32_16x16x32_bf16 v[116:119], v[202:205], v[170:173], v[116:119]
	v_mfma_f32_16x16x32_bf16 v[112:115], v[210:213], v[170:173], v[112:115]
	v_mfma_f32_16x16x32_bf16 v[100:103], v[202:205], v[178:181], v[100:103]
	v_mfma_f32_16x16x32_bf16 v[96:99], v[210:213], v[178:181], v[96:99]
	v_mfma_f32_16x16x32_bf16 v[84:87], v[202:205], v[186:189], v[84:87]
	v_mfma_f32_16x16x32_bf16 v[80:83], v[210:213], v[186:189], v[80:83]
	v_mfma_f32_16x16x32_bf16 v[68:71], v[202:205], v[194:197], v[68:71]
	v_mfma_f32_16x16x32_bf16 v[64:67], v[210:213], v[194:197], v[64:67]
	v_mfma_f32_16x16x32_bf16 v[116:119], v[206:209], v[174:177], v[116:119]
	v_mfma_f32_16x16x32_bf16 v[112:115], v[214:217], v[174:177], v[112:115]
	v_mfma_f32_16x16x32_bf16 v[100:103], v[206:209], v[182:185], v[100:103]
	v_mfma_f32_16x16x32_bf16 v[96:99], v[214:217], v[182:185], v[96:99]
	v_mfma_f32_16x16x32_bf16 v[84:87], v[206:209], v[190:193], v[84:87]
	v_mfma_f32_16x16x32_bf16 v[80:83], v[214:217], v[190:193], v[80:83]
	v_mfma_f32_16x16x32_bf16 v[68:71], v[206:209], v[198:201], v[68:71]
	v_mfma_f32_16x16x32_bf16 v[64:67], v[214:217], v[198:201], v[64:67]
	s_setprio 0
	s_mov_b32 m0, s61
	v_lshl_add_u64 v[220:221], s[54:55], 0, v[130:131]
	s_barrier
	ds_read_b128 v[170:173], v154 offset:16384
	ds_read_b128 v[174:177], v154 offset:17408
	ds_read_b128 v[178:181], v154 offset:18432
	ds_read_b128 v[182:185], v154 offset:19456
	ds_read_b128 v[186:189], v154 offset:20480
	ds_read_b128 v[190:193], v154 offset:21504
	ds_read_b128 v[194:197], v154 offset:22528
	ds_read_b128 v[198:201], v154 offset:23552
	global_load_lds_dwordx4 v[220:221], off
	v_lshl_add_u64 v[222:223], s[54:55], 0, v[132:133]
	s_mov_b32 m0, s62
	s_nop 0
	global_load_lds_dwordx4 v[222:223], off
	s_barrier
	s_waitcnt lgkmcnt(0)
	s_setprio 1
	s_waitcnt lgkmcnt(0)
	v_mfma_f32_16x16x32_bf16 v[60:63], v[146:149], v[170:173], v[60:63]
	v_mfma_f32_16x16x32_bf16 v[56:59], v[162:165], v[170:173], v[56:59]
	v_mfma_f32_16x16x32_bf16 v[44:47], v[146:149], v[178:181], v[44:47]
	v_mfma_f32_16x16x32_bf16 v[40:43], v[162:165], v[178:181], v[40:43]
	v_mfma_f32_16x16x32_bf16 v[28:31], v[146:149], v[186:189], v[28:31]
	v_mfma_f32_16x16x32_bf16 v[24:27], v[162:165], v[186:189], v[24:27]
	v_mfma_f32_16x16x32_bf16 v[12:15], v[146:149], v[194:197], v[12:15]
	v_mfma_f32_16x16x32_bf16 v[8:11], v[162:165], v[194:197], v[8:11]
	v_mfma_f32_16x16x32_bf16 v[60:63], v[158:161], v[174:177], v[60:63]
	v_mfma_f32_16x16x32_bf16 v[56:59], v[166:169], v[174:177], v[56:59]
	v_mfma_f32_16x16x32_bf16 v[44:47], v[158:161], v[182:185], v[44:47]
	v_mfma_f32_16x16x32_bf16 v[40:43], v[166:169], v[182:185], v[40:43]
	v_mfma_f32_16x16x32_bf16 v[28:31], v[158:161], v[190:193], v[28:31]
	v_mfma_f32_16x16x32_bf16 v[24:27], v[166:169], v[190:193], v[24:27]
	v_mfma_f32_16x16x32_bf16 v[12:15], v[158:161], v[198:201], v[12:15]
	v_mfma_f32_16x16x32_bf16 v[8:11], v[166:169], v[198:201], v[8:11]
	s_setprio 0
	s_barrier
	s_add_i32 s81, s71, s60
	v_lshl_add_u64 v[146:147], v[218:219], 0, s[14:15]
	s_mov_b32 m0, s81
	s_nop 0
	global_load_lds_dwordx4 v[146:147], off
	v_lshl_add_u64 v[146:147], v[218:219], 0, s[18:19]
	s_add_i32 m0, s81, 0x2000
	s_nop 0
	global_load_lds_dwordx4 v[146:147], off
	s_waitcnt vmcnt(6)
	s_barrier
	s_setprio 1
	v_mfma_f32_16x16x32_bf16 v[52:55], v[202:205], v[170:173], v[52:55]
	v_mfma_f32_16x16x32_bf16 v[48:51], v[210:213], v[170:173], v[48:51]
	v_mfma_f32_16x16x32_bf16 v[36:39], v[202:205], v[178:181], v[36:39]
	v_mfma_f32_16x16x32_bf16 v[32:35], v[210:213], v[178:181], v[32:35]
	v_mfma_f32_16x16x32_bf16 v[20:23], v[202:205], v[186:189], v[20:23]
	v_mfma_f32_16x16x32_bf16 v[16:19], v[210:213], v[186:189], v[16:19]
	v_mfma_f32_16x16x32_bf16 v[4:7], v[202:205], v[194:197], v[4:7]
	v_mfma_f32_16x16x32_bf16 v[0:3], v[210:213], v[194:197], v[0:3]
	v_mfma_f32_16x16x32_bf16 v[52:55], v[206:209], v[174:177], v[52:55]
	v_mfma_f32_16x16x32_bf16 v[48:51], v[214:217], v[174:177], v[48:51]
	v_mfma_f32_16x16x32_bf16 v[36:39], v[206:209], v[182:185], v[36:39]
	v_mfma_f32_16x16x32_bf16 v[32:35], v[214:217], v[182:185], v[32:35]
	v_mfma_f32_16x16x32_bf16 v[20:23], v[206:209], v[190:193], v[20:23]
	v_mfma_f32_16x16x32_bf16 v[16:19], v[214:217], v[190:193], v[16:19]
	v_mfma_f32_16x16x32_bf16 v[4:7], v[206:209], v[198:201], v[4:7]
	v_mfma_f32_16x16x32_bf16 v[0:3], v[214:217], v[198:201], v[0:3]
	s_setprio 0
	s_add_i32 s81, 0, 0x18000
	v_add_u32_e32 v134, s81, v151
	s_barrier
	ds_read_b128 v[146:149], v134
	ds_read_b128 v[158:161], v134 offset:1024
	ds_read_b128 v[162:165], v134 offset:2048
	ds_read_b128 v[166:169], v134 offset:3072
	s_add_u32 s54, s54, 0x80000
	s_addc_u32 s55, s55, 0
	s_mov_b32 m0, s63
	v_lshl_add_u64 v[202:203], s[54:55], 0, v[130:131]
	ds_read_b128 v[170:173], v154 offset:32768
	ds_read_b128 v[174:177], v154 offset:33792
	ds_read_b128 v[178:181], v154 offset:34816
	ds_read_b128 v[182:185], v154 offset:35840
	ds_read_b128 v[186:189], v154 offset:36864
	ds_read_b128 v[190:193], v154 offset:37888
	ds_read_b128 v[194:197], v154 offset:38912
	ds_read_b128 v[198:201], v154 offset:39936
	global_load_lds_dwordx4 v[202:203], off
	v_lshl_add_u64 v[202:203], s[54:55], 0, v[132:133]
	s_mov_b32 m0, s64
	s_nop 0
	global_load_lds_dwordx4 v[202:203], off
	s_waitcnt lgkmcnt(8)
	s_barrier
	s_waitcnt lgkmcnt(0)
	s_setprio 1
	s_waitcnt lgkmcnt(0)
	v_mfma_f32_16x16x32_bf16 v[124:127], v[146:149], v[170:173], v[124:127]
	v_mfma_f32_16x16x32_bf16 v[120:123], v[162:165], v[170:173], v[120:123]
	v_mfma_f32_16x16x32_bf16 v[108:111], v[146:149], v[178:181], v[108:111]
	v_mfma_f32_16x16x32_bf16 v[104:107], v[162:165], v[178:181], v[104:107]
	v_mfma_f32_16x16x32_bf16 v[92:95], v[146:149], v[186:189], v[92:95]
	v_mfma_f32_16x16x32_bf16 v[88:91], v[162:165], v[186:189], v[88:91]
	v_mfma_f32_16x16x32_bf16 v[76:79], v[146:149], v[194:197], v[76:79]
	v_mfma_f32_16x16x32_bf16 v[72:75], v[162:165], v[194:197], v[72:75]
	v_mfma_f32_16x16x32_bf16 v[124:127], v[158:161], v[174:177], v[124:127]
	v_mfma_f32_16x16x32_bf16 v[120:123], v[166:169], v[174:177], v[120:123]
	v_mfma_f32_16x16x32_bf16 v[108:111], v[158:161], v[182:185], v[108:111]
	v_mfma_f32_16x16x32_bf16 v[104:107], v[166:169], v[182:185], v[104:107]
	v_mfma_f32_16x16x32_bf16 v[92:95], v[158:161], v[190:193], v[92:95]
	v_mfma_f32_16x16x32_bf16 v[88:91], v[166:169], v[190:193], v[88:91]
	v_mfma_f32_16x16x32_bf16 v[76:79], v[158:161], v[198:201], v[76:79]
	v_mfma_f32_16x16x32_bf16 v[72:75], v[166:169], v[198:201], v[72:75]
	s_setprio 0
	s_barrier
	s_add_i32 s54, 0, 0x1c000
	s_add_i32 s55, s81, s60
	v_add_u32_e32 v134, s54, v151
	v_lshl_add_u64 v[224:225], v[218:219], 0, s[26:27]
	s_mov_b32 m0, s55
	ds_read_b128 v[202:205], v134
	ds_read_b128 v[206:209], v134 offset:1024
	ds_read_b128 v[210:213], v134 offset:2048
	ds_read_b128 v[214:217], v134 offset:3072
	global_load_lds_dwordx4 v[224:225], off
	v_lshl_add_u64 v[224:225], v[218:219], 0, s[28:29]
	s_add_i32 m0, s55, 0x2000
	s_nop 0
	global_load_lds_dwordx4 v[224:225], off
	s_barrier
	s_waitcnt lgkmcnt(0)
	s_setprio 1
	s_waitcnt lgkmcnt(0)
	v_mfma_f32_16x16x32_bf16 v[116:119], v[202:205], v[170:173], v[116:119]
	v_mfma_f32_16x16x32_bf16 v[112:115], v[210:213], v[170:173], v[112:115]
	v_mfma_f32_16x16x32_bf16 v[100:103], v[202:205], v[178:181], v[100:103]
	v_mfma_f32_16x16x32_bf16 v[96:99], v[210:213], v[178:181], v[96:99]
	v_mfma_f32_16x16x32_bf16 v[84:87], v[202:205], v[186:189], v[84:87]
	v_mfma_f32_16x16x32_bf16 v[80:83], v[210:213], v[186:189], v[80:83]
	v_mfma_f32_16x16x32_bf16 v[68:71], v[202:205], v[194:197], v[68:71]
	v_mfma_f32_16x16x32_bf16 v[64:67], v[210:213], v[194:197], v[64:67]
	v_mfma_f32_16x16x32_bf16 v[116:119], v[206:209], v[174:177], v[116:119]
	v_mfma_f32_16x16x32_bf16 v[112:115], v[214:217], v[174:177], v[112:115]
	v_mfma_f32_16x16x32_bf16 v[100:103], v[206:209], v[182:185], v[100:103]
	v_mfma_f32_16x16x32_bf16 v[96:99], v[214:217], v[182:185], v[96:99]
	v_mfma_f32_16x16x32_bf16 v[84:87], v[206:209], v[190:193], v[84:87]
	v_mfma_f32_16x16x32_bf16 v[80:83], v[214:217], v[190:193], v[80:83]
	v_mfma_f32_16x16x32_bf16 v[68:71], v[206:209], v[198:201], v[68:71]
	v_mfma_f32_16x16x32_bf16 v[64:67], v[214:217], v[198:201], v[64:67]
	s_setprio 0
	s_mov_b32 m0, s66
	v_lshl_add_u64 v[220:221], v[220:221], 0, s[30:31]
	s_barrier
	ds_read_b128 v[170:173], v154 offset:49152
	ds_read_b128 v[174:177], v154 offset:50176
	ds_read_b128 v[178:181], v154 offset:51200
	ds_read_b128 v[182:185], v154 offset:52224
	ds_read_b128 v[186:189], v154 offset:53248
	ds_read_b128 v[190:193], v154 offset:54272
	ds_read_b128 v[194:197], v154 offset:55296
	ds_read_b128 v[198:201], v154 offset:56320
	global_load_lds_dwordx4 v[220:221], off
	v_lshl_add_u64 v[220:221], v[222:223], 0, s[30:31]
	s_mov_b32 m0, s67
	s_nop 0
	global_load_lds_dwordx4 v[220:221], off
	s_barrier
	s_waitcnt lgkmcnt(0)
	s_setprio 1
	s_waitcnt lgkmcnt(0)
	v_mfma_f32_16x16x32_bf16 v[60:63], v[146:149], v[170:173], v[60:63]
	v_mfma_f32_16x16x32_bf16 v[56:59], v[162:165], v[170:173], v[56:59]
	v_mfma_f32_16x16x32_bf16 v[44:47], v[146:149], v[178:181], v[44:47]
	v_mfma_f32_16x16x32_bf16 v[40:43], v[162:165], v[178:181], v[40:43]
	v_mfma_f32_16x16x32_bf16 v[28:31], v[146:149], v[186:189], v[28:31]
	v_mfma_f32_16x16x32_bf16 v[24:27], v[162:165], v[186:189], v[24:27]
	v_mfma_f32_16x16x32_bf16 v[12:15], v[146:149], v[194:197], v[12:15]
	v_mfma_f32_16x16x32_bf16 v[8:11], v[162:165], v[194:197], v[8:11]
	v_mfma_f32_16x16x32_bf16 v[60:63], v[158:161], v[174:177], v[60:63]
	v_mfma_f32_16x16x32_bf16 v[56:59], v[166:169], v[174:177], v[56:59]
	v_mfma_f32_16x16x32_bf16 v[44:47], v[158:161], v[182:185], v[44:47]
	v_mfma_f32_16x16x32_bf16 v[40:43], v[166:169], v[182:185], v[40:43]
	v_mfma_f32_16x16x32_bf16 v[28:31], v[158:161], v[190:193], v[28:31]
	v_mfma_f32_16x16x32_bf16 v[24:27], v[166:169], v[190:193], v[24:27]
	v_mfma_f32_16x16x32_bf16 v[12:15], v[158:161], v[198:201], v[12:15]
	v_mfma_f32_16x16x32_bf16 v[8:11], v[166:169], v[198:201], v[8:11]
	s_setprio 0
	s_barrier
	s_add_i32 s54, s54, s60
	v_lshl_add_u64 v[146:147], v[218:219], 0, s[34:35]
	s_mov_b32 m0, s54
	s_nop 0
	global_load_lds_dwordx4 v[146:147], off
	v_lshl_add_u64 v[146:147], v[218:219], 0, s[38:39]
	s_add_i32 m0, s54, 0x2000
	s_nop 0
	global_load_lds_dwordx4 v[146:147], off
	s_waitcnt vmcnt(6)
	s_barrier
	s_setprio 1
	v_mfma_f32_16x16x32_bf16 v[52:55], v[202:205], v[170:173], v[52:55]
	v_mfma_f32_16x16x32_bf16 v[48:51], v[210:213], v[170:173], v[48:51]
	v_mfma_f32_16x16x32_bf16 v[36:39], v[202:205], v[178:181], v[36:39]
	v_mfma_f32_16x16x32_bf16 v[32:35], v[210:213], v[178:181], v[32:35]
	v_mfma_f32_16x16x32_bf16 v[20:23], v[202:205], v[186:189], v[20:23]
	v_mfma_f32_16x16x32_bf16 v[16:19], v[210:213], v[186:189], v[16:19]
	v_mfma_f32_16x16x32_bf16 v[4:7], v[202:205], v[194:197], v[4:7]
	v_mfma_f32_16x16x32_bf16 v[0:3], v[210:213], v[194:197], v[0:3]
	v_mfma_f32_16x16x32_bf16 v[52:55], v[206:209], v[174:177], v[52:55]
	v_mfma_f32_16x16x32_bf16 v[48:51], v[214:217], v[174:177], v[48:51]
	v_mfma_f32_16x16x32_bf16 v[36:39], v[206:209], v[182:185], v[36:39]
	v_mfma_f32_16x16x32_bf16 v[32:35], v[214:217], v[182:185], v[32:35]
	v_mfma_f32_16x16x32_bf16 v[20:23], v[206:209], v[190:193], v[20:23]
	v_mfma_f32_16x16x32_bf16 v[16:19], v[214:217], v[190:193], v[16:19]
	v_mfma_f32_16x16x32_bf16 v[4:7], v[206:209], v[198:201], v[4:7]
	v_mfma_f32_16x16x32_bf16 v[0:3], v[214:217], v[198:201], v[0:3]
	s_setprio 0
	s_add_i32 s80, s80, 2
	s_add_u32 s78, s78, 0x8000
	s_addc_u32 s79, s79, 0
	s_add_u32 s52, s52, 0x100
	s_addc_u32 s53, s53, 0
	s_cmp_gt_u32 s80, 29
	s_barrier
	s_cbranch_scc0 .LBB0_1153
	s_lshl_b32 s45, s50, 21
	s_add_u32 s100, s20, s45
	s_addc_u32 s101, s21, 0
	s_add_u32 s98, s8, s45
	s_addc_u32 s99, s9, 0
	s_cmp_eq_u32 s50, 64
	s_cselect_b32 s98, s10, s98
	s_cselect_b32 s99, s11, s99
	s_lshl_b32 s45, s50, 20
	s_add_u32 s52, s22, s45
	s_addc_u32 s53, s23, 0
	v_and_b32_e32 v134, 8, v150
	v_and_b32_e32 v146, 0xfff7, v150
	v_lshl_add_u32 v147, v134, 1, v152
	s_lshl_b32 s45, s75, 8
	v_cmp_ne_u32_e32 vcc, 0, v134
	v_add_u32_e32 v147, s45, v147
	v_lshlrev_b32_e32 v146, 13, v146
	v_lshl_add_u32 v146, v147, 2, v146
	s_lshl_b32 s51, s50, 10
	s_cmp_eq_u32 s50, 64
	s_cselect_b32 s45, 1, 0
	s_add_u32 s50, s24, s51
	s_addc_u32 s51, s25, 0
	s_cmp_eq_u32 s45, 1
	s_cbranch_scc1 .Lepo_tail
	v_mov_b32_e32 v166, v146
	v_add_u32_e32 v167, 0x10000, v146
	global_load_dwordx4 v[170:173], v166, s[98:99]
	global_load_dwordx4 v[174:177], v167, s[98:99]
	global_load_dwordx4 v[178:181], v166, s[98:99] offset:512
	global_load_dwordx4 v[182:185], v167, s[98:99] offset:512
	v_add_u32_e32 v166, 0x20000, v146
	v_add_u32_e32 v167, 0x30000, v146
	global_load_dwordx4 v[186:189], v166, s[98:99]
	global_load_dwordx4 v[190:193], v167, s[98:99]
	global_load_dwordx4 v[194:197], v166, s[98:99] offset:512
	global_load_dwordx4 v[198:201], v167, s[98:99] offset:512
	v_add_u32_e32 v166, 0x40000, v146
	v_add_u32_e32 v167, 0x50000, v146
	global_load_dwordx4 v[202:205], v166, s[98:99]
	global_load_dwordx4 v[206:209], v167, s[98:99]
	global_load_dwordx4 v[210:213], v166, s[98:99] offset:512
	global_load_dwordx4 v[214:217], v167, s[98:99] offset:512
	v_mov_b32_e32 v158, v120
	v_mov_b32_e32 v159, v121
	v_mov_b32_e32 v160, v122
	v_mov_b32_e32 v161, v123
	v_mov_b32_e32 v162, v112
	v_mov_b32_e32 v163, v113
	v_mov_b32_e32 v164, v114
	v_mov_b32_e32 v165, v115
	v_mov_b32_dpp v120, v124 row_ror:8 row_mask:0xf bank_mask:0x3
	v_mov_b32_dpp v121, v125 row_ror:8 row_mask:0xf bank_mask:0x3
	v_mov_b32_dpp v122, v126 row_ror:8 row_mask:0xf bank_mask:0x3
	v_mov_b32_dpp v123, v127 row_ror:8 row_mask:0xf bank_mask:0x3
	v_mov_b32_dpp v112, v116 row_ror:8 row_mask:0xf bank_mask:0x3
	v_mov_b32_dpp v113, v117 row_ror:8 row_mask:0xf bank_mask:0x3
	v_mov_b32_dpp v114, v118 row_ror:8 row_mask:0xf bank_mask:0x3
	v_mov_b32_dpp v115, v119 row_ror:8 row_mask:0xf bank_mask:0x3
	v_mov_b32_dpp v124, v158 row_ror:8 row_mask:0xf bank_mask:0xc
	v_mov_b32_dpp v125, v159 row_ror:8 row_mask:0xf bank_mask:0xc
	v_mov_b32_dpp v126, v160 row_ror:8 row_mask:0xf bank_mask:0xc
	v_mov_b32_dpp v127, v161 row_ror:8 row_mask:0xf bank_mask:0xc
	v_mov_b32_dpp v116, v162 row_ror:8 row_mask:0xf bank_mask:0xc
	v_mov_b32_dpp v117, v163 row_ror:8 row_mask:0xf bank_mask:0xc
	v_mov_b32_dpp v118, v164 row_ror:8 row_mask:0xf bank_mask:0xc
	v_mov_b32_dpp v119, v165 row_ror:8 row_mask:0xf bank_mask:0xc
	v_mov_b32_e32 v166, v146
	v_add_u32_e32 v167, 0x10000, v146
	v_lshrrev_b32_e32 v168, 1, v166
	v_lshrrev_b32_e32 v169, 1, v167
	s_waitcnt vmcnt(8)
	v_pk_add_f32 v[124:125], v[124:125], v[170:171]
	v_pk_add_f32 v[126:127], v[126:127], v[172:173]
	v_pk_add_f32 v[120:121], v[120:121], v[174:175]
	v_pk_add_f32 v[122:123], v[122:123], v[176:177]
	v_pk_add_f32 v[116:117], v[116:117], v[178:179]
	v_pk_add_f32 v[118:119], v[118:119], v[180:181]
	v_pk_add_f32 v[112:113], v[112:113], v[182:183]
	v_pk_add_f32 v[114:115], v[114:115], v[184:185]
	global_store_dwordx4 v166, v[124:127], s[100:101]
	global_store_dwordx4 v167, v[120:123], s[100:101]
	global_store_dwordx4 v166, v[116:119], s[100:101] offset:512
	global_store_dwordx4 v167, v[112:115], s[100:101] offset:512
	v_cvt_pk_bf16_f32 v158, v124, v125
	v_cvt_pk_bf16_f32 v159, v126, v127
	v_cvt_pk_bf16_f32 v160, v120, v121
	v_cvt_pk_bf16_f32 v161, v122, v123
	v_cvt_pk_bf16_f32 v162, v116, v117
	v_cvt_pk_bf16_f32 v163, v118, v119
	v_cvt_pk_bf16_f32 v164, v112, v113
	v_cvt_pk_bf16_f32 v165, v114, v115
	global_store_dwordx2 v168, v[158:159], s[52:53]
	global_store_dwordx2 v169, v[160:161], s[52:53]
	global_store_dwordx2 v168, v[162:163], s[52:53] offset:256
	global_store_dwordx2 v169, v[164:165], s[52:53] offset:256
	v_mul_f32_e32 v148, v124, v124
	v_mul_f32_e32 v149, v120, v120
	v_fmac_f32_e32 v148, v125, v125
	v_fmac_f32_e32 v149, v121, v121
	v_fmac_f32_e32 v148, v126, v126
	v_fmac_f32_e32 v149, v122, v122
	v_fmac_f32_e32 v148, v127, v127
	v_fmac_f32_e32 v149, v123, v123
	v_fmac_f32_e32 v148, v116, v116
	v_fmac_f32_e32 v149, v112, v112
	v_fmac_f32_e32 v148, v117, v117
	v_fmac_f32_e32 v149, v113, v113
	v_fmac_f32_e32 v148, v118, v118
	v_fmac_f32_e32 v149, v114, v114
	v_fmac_f32_e32 v148, v119, v119
	v_fmac_f32_e32 v149, v115, v115
	s_nop 1
	v_add_f32_dpp v148, v148, v148 row_ror:8 row_mask:0xf bank_mask:0xf
	v_add_f32_dpp v149, v149, v149 row_ror:8 row_mask:0xf bank_mask:0xf
	v_mov_b32_e32 v134, v148
	v_mov_b32_e32 v147, v149
	s_nop 1
	v_permlane16_swap_b32_e32 v148, v134
	v_permlane16_swap_b32_e32 v149, v147
	v_add_f32_e32 v148, v148, v134
	v_add_f32_e32 v149, v149, v147
	v_mov_b32_e32 v134, v148
	v_mov_b32_e32 v147, v149
	s_nop 1
	v_permlane32_swap_b32_e32 v148, v134
	v_permlane32_swap_b32_e32 v149, v147
	v_add_f32_e32 v148, v148, v134
	v_add_f32_e32 v149, v149, v147
	v_cndmask_b32_e32 v148, v148, v149, vcc
	v_lshlrev_b32_e32 v134, 2, v150
	s_mov_b64 exec, s[4:5]
	global_atomic_add_f32 v134, v148, s[50:51]
	s_mov_b64 exec, -1
	v_add_u32_e32 v166, 0x60000, v146
	v_add_u32_e32 v167, 0x70000, v146
	global_load_dwordx4 v[170:173], v166, s[98:99]
	global_load_dwordx4 v[174:177], v167, s[98:99]
	global_load_dwordx4 v[178:181], v166, s[98:99] offset:512
	global_load_dwordx4 v[182:185], v167, s[98:99] offset:512
	v_mov_b32_e32 v158, v104
	v_mov_b32_e32 v159, v105
	v_mov_b32_e32 v160, v106
	v_mov_b32_e32 v161, v107
	v_mov_b32_e32 v162, v96
	v_mov_b32_e32 v163, v97
	v_mov_b32_e32 v164, v98
	v_mov_b32_e32 v165, v99
	v_mov_b32_dpp v104, v108 row_ror:8 row_mask:0xf bank_mask:0x3
	v_mov_b32_dpp v105, v109 row_ror:8 row_mask:0xf bank_mask:0x3
	v_mov_b32_dpp v106, v110 row_ror:8 row_mask:0xf bank_mask:0x3
	v_mov_b32_dpp v107, v111 row_ror:8 row_mask:0xf bank_mask:0x3
	v_mov_b32_dpp v96, v100 row_ror:8 row_mask:0xf bank_mask:0x3
	v_mov_b32_dpp v97, v101 row_ror:8 row_mask:0xf bank_mask:0x3
	v_mov_b32_dpp v98, v102 row_ror:8 row_mask:0xf bank_mask:0x3
	v_mov_b32_dpp v99, v103 row_ror:8 row_mask:0xf bank_mask:0x3
	v_mov_b32_dpp v108, v158 row_ror:8 row_mask:0xf bank_mask:0xc
	v_mov_b32_dpp v109, v159 row_ror:8 row_mask:0xf bank_mask:0xc
	v_mov_b32_dpp v110, v160 row_ror:8 row_mask:0xf bank_mask:0xc
	v_mov_b32_dpp v111, v161 row_ror:8 row_mask:0xf bank_mask:0xc
	v_mov_b32_dpp v100, v162 row_ror:8 row_mask:0xf bank_mask:0xc
	v_mov_b32_dpp v101, v163 row_ror:8 row_mask:0xf bank_mask:0xc
	v_mov_b32_dpp v102, v164 row_ror:8 row_mask:0xf bank_mask:0xc
	v_mov_b32_dpp v103, v165 row_ror:8 row_mask:0xf bank_mask:0xc
	v_add_u32_e32 v166, 0x20000, v146
	v_add_u32_e32 v167, 0x30000, v146
	v_lshrrev_b32_e32 v168, 1, v166
	v_lshrrev_b32_e32 v169, 1, v167
	s_waitcnt vmcnt(17)
	v_pk_add_f32 v[108:109], v[108:109], v[186:187]
	v_pk_add_f32 v[110:111], v[110:111], v[188:189]
	v_pk_add_f32 v[104:105], v[104:105], v[190:191]
	v_pk_add_f32 v[106:107], v[106:107], v[192:193]
	v_pk_add_f32 v[100:101], v[100:101], v[194:195]
	v_pk_add_f32 v[102:103], v[102:103], v[196:197]
	v_pk_add_f32 v[96:97], v[96:97], v[198:199]
	v_pk_add_f32 v[98:99], v[98:99], v[200:201]
	global_store_dwordx4 v166, v[108:111], s[100:101]
	global_store_dwordx4 v167, v[104:107], s[100:101]
	global_store_dwordx4 v166, v[100:103], s[100:101] offset:512
	global_store_dwordx4 v167, v[96:99], s[100:101] offset:512
	v_cvt_pk_bf16_f32 v158, v108, v109
	v_cvt_pk_bf16_f32 v159, v110, v111
	v_cvt_pk_bf16_f32 v160, v104, v105
	v_cvt_pk_bf16_f32 v161, v106, v107
	v_cvt_pk_bf16_f32 v162, v100, v101
	v_cvt_pk_bf16_f32 v163, v102, v103
	v_cvt_pk_bf16_f32 v164, v96, v97
	v_cvt_pk_bf16_f32 v165, v98, v99
	global_store_dwordx2 v168, v[158:159], s[52:53]
	global_store_dwordx2 v169, v[160:161], s[52:53]
	global_store_dwordx2 v168, v[162:163], s[52:53] offset:256
	global_store_dwordx2 v169, v[164:165], s[52:53] offset:256
	v_mul_f32_e32 v148, v108, v108
	v_mul_f32_e32 v149, v104, v104
	v_fmac_f32_e32 v148, v109, v109
	v_fmac_f32_e32 v149, v105, v105
	v_fmac_f32_e32 v148, v110, v110
	v_fmac_f32_e32 v149, v106, v106
	v_fmac_f32_e32 v148, v111, v111
	v_fmac_f32_e32 v149, v107, v107
	v_fmac_f32_e32 v148, v100, v100
	v_fmac_f32_e32 v149, v96, v96
	v_fmac_f32_e32 v148, v101, v101
	v_fmac_f32_e32 v149, v97, v97
	v_fmac_f32_e32 v148, v102, v102
	v_fmac_f32_e32 v149, v98, v98
	v_fmac_f32_e32 v148, v103, v103
	v_fmac_f32_e32 v149, v99, v99
	s_nop 1
	v_add_f32_dpp v148, v148, v148 row_ror:8 row_mask:0xf bank_mask:0xf
	v_add_f32_dpp v149, v149, v149 row_ror:8 row_mask:0xf bank_mask:0xf
	v_mov_b32_e32 v134, v148
	v_mov_b32_e32 v147, v149
	s_nop 1
	v_permlane16_swap_b32_e32 v148, v134
	v_permlane16_swap_b32_e32 v149, v147
	v_add_f32_e32 v148, v148, v134
	v_add_f32_e32 v149, v149, v147
	v_mov_b32_e32 v134, v148
	v_mov_b32_e32 v147, v149
	s_nop 1
	v_permlane32_swap_b32_e32 v148, v134
	v_permlane32_swap_b32_e32 v149, v147
	v_add_f32_e32 v148, v148, v134
	v_add_f32_e32 v149, v149, v147
	v_cndmask_b32_e32 v148, v148, v149, vcc
	v_lshlrev_b32_e32 v134, 2, v150
	s_mov_b64 exec, s[4:5]
	global_atomic_add_f32 v134, v148, s[50:51] offset:64
	s_mov_b64 exec, -1
	v_add_u32_e32 v166, 0x100000, v146
	v_add_u32_e32 v167, 0x110000, v146
	global_load_dwordx4 v[186:189], v166, s[98:99]
	global_load_dwordx4 v[190:193], v167, s[98:99]
	global_load_dwordx4 v[194:197], v166, s[98:99] offset:512
	global_load_dwordx4 v[198:201], v167, s[98:99] offset:512
	v_mov_b32_e32 v158, v88
	v_mov_b32_e32 v159, v89
	v_mov_b32_e32 v160, v90
	v_mov_b32_e32 v161, v91
	v_mov_b32_e32 v162, v80
	v_mov_b32_e32 v163, v81
	v_mov_b32_e32 v164, v82
	v_mov_b32_e32 v165, v83
	v_mov_b32_dpp v88, v92 row_ror:8 row_mask:0xf bank_mask:0x3
	v_mov_b32_dpp v89, v93 row_ror:8 row_mask:0xf bank_mask:0x3
	v_mov_b32_dpp v90, v94 row_ror:8 row_mask:0xf bank_mask:0x3
	v_mov_b32_dpp v91, v95 row_ror:8 row_mask:0xf bank_mask:0x3
	v_mov_b32_dpp v80, v84 row_ror:8 row_mask:0xf bank_mask:0x3
	v_mov_b32_dpp v81, v85 row_ror:8 row_mask:0xf bank_mask:0x3
	v_mov_b32_dpp v82, v86 row_ror:8 row_mask:0xf bank_mask:0x3
	v_mov_b32_dpp v83, v87 row_ror:8 row_mask:0xf bank_mask:0x3
	v_mov_b32_dpp v92, v158 row_ror:8 row_mask:0xf bank_mask:0xc
	v_mov_b32_dpp v93, v159 row_ror:8 row_mask:0xf bank_mask:0xc
	v_mov_b32_dpp v94, v160 row_ror:8 row_mask:0xf bank_mask:0xc
	v_mov_b32_dpp v95, v161 row_ror:8 row_mask:0xf bank_mask:0xc
	v_mov_b32_dpp v84, v162 row_ror:8 row_mask:0xf bank_mask:0xc
	v_mov_b32_dpp v85, v163 row_ror:8 row_mask:0xf bank_mask:0xc
	v_mov_b32_dpp v86, v164 row_ror:8 row_mask:0xf bank_mask:0xc
	v_mov_b32_dpp v87, v165 row_ror:8 row_mask:0xf bank_mask:0xc
	v_add_u32_e32 v166, 0x40000, v146
	v_add_u32_e32 v167, 0x50000, v146
	v_lshrrev_b32_e32 v168, 1, v166
	v_lshrrev_b32_e32 v169, 1, v167
	s_waitcnt vmcnt(26)
	v_pk_add_f32 v[92:93], v[92:93], v[202:203]
	v_pk_add_f32 v[94:95], v[94:95], v[204:205]
	v_pk_add_f32 v[88:89], v[88:89], v[206:207]
	v_pk_add_f32 v[90:91], v[90:91], v[208:209]
	v_pk_add_f32 v[84:85], v[84:85], v[210:211]
	v_pk_add_f32 v[86:87], v[86:87], v[212:213]
	v_pk_add_f32 v[80:81], v[80:81], v[214:215]
	v_pk_add_f32 v[82:83], v[82:83], v[216:217]
	global_store_dwordx4 v166, v[92:95], s[100:101]
	global_store_dwordx4 v167, v[88:91], s[100:101]
	global_store_dwordx4 v166, v[84:87], s[100:101] offset:512
	global_store_dwordx4 v167, v[80:83], s[100:101] offset:512
	v_cvt_pk_bf16_f32 v158, v92, v93
	v_cvt_pk_bf16_f32 v159, v94, v95
	v_cvt_pk_bf16_f32 v160, v88, v89
	v_cvt_pk_bf16_f32 v161, v90, v91
	v_cvt_pk_bf16_f32 v162, v84, v85
	v_cvt_pk_bf16_f32 v163, v86, v87
	v_cvt_pk_bf16_f32 v164, v80, v81
	v_cvt_pk_bf16_f32 v165, v82, v83
	global_store_dwordx2 v168, v[158:159], s[52:53]
	global_store_dwordx2 v169, v[160:161], s[52:53]
	global_store_dwordx2 v168, v[162:163], s[52:53] offset:256
	global_store_dwordx2 v169, v[164:165], s[52:53] offset:256
	v_mul_f32_e32 v148, v92, v92
	v_mul_f32_e32 v149, v88, v88
	v_fmac_f32_e32 v148, v93, v93
	v_fmac_f32_e32 v149, v89, v89
	v_fmac_f32_e32 v148, v94, v94
	v_fmac_f32_e32 v149, v90, v90
	v_fmac_f32_e32 v148, v95, v95
	v_fmac_f32_e32 v149, v91, v91
	v_fmac_f32_e32 v148, v84, v84
	v_fmac_f32_e32 v149, v80, v80
	v_fmac_f32_e32 v148, v85, v85
	v_fmac_f32_e32 v149, v81, v81
	v_fmac_f32_e32 v148, v86, v86
	v_fmac_f32_e32 v149, v82, v82
	v_fmac_f32_e32 v148, v87, v87
	v_fmac_f32_e32 v149, v83, v83
	s_nop 1
	v_add_f32_dpp v148, v148, v148 row_ror:8 row_mask:0xf bank_mask:0xf
	v_add_f32_dpp v149, v149, v149 row_ror:8 row_mask:0xf bank_mask:0xf
	v_mov_b32_e32 v134, v148
	v_mov_b32_e32 v147, v149
	s_nop 1
	v_permlane16_swap_b32_e32 v148, v134
	v_permlane16_swap_b32_e32 v149, v147
	v_add_f32_e32 v148, v148, v134
	v_add_f32_e32 v149, v149, v147
	v_mov_b32_e32 v134, v148
	v_mov_b32_e32 v147, v149
	s_nop 1
	v_permlane32_swap_b32_e32 v148, v134
	v_permlane32_swap_b32_e32 v149, v147
	v_add_f32_e32 v148, v148, v134
	v_add_f32_e32 v149, v149, v147
	v_cndmask_b32_e32 v148, v148, v149, vcc
	v_lshlrev_b32_e32 v134, 2, v150
	s_mov_b64 exec, s[4:5]
	global_atomic_add_f32 v134, v148, s[50:51] offset:128
	s_mov_b64 exec, -1
	v_add_u32_e32 v166, 0x120000, v146
	v_add_u32_e32 v167, 0x130000, v146
	global_load_dwordx4 v[202:205], v166, s[98:99]
	global_load_dwordx4 v[206:209], v167, s[98:99]
	global_load_dwordx4 v[210:213], v166, s[98:99] offset:512
	global_load_dwordx4 v[214:217], v167, s[98:99] offset:512
	v_mov_b32_e32 v158, v72
	v_mov_b32_e32 v159, v73
	v_mov_b32_e32 v160, v74
	v_mov_b32_e32 v161, v75
	v_mov_b32_e32 v162, v64
	v_mov_b32_e32 v163, v65
	v_mov_b32_e32 v164, v66
	v_mov_b32_e32 v165, v67
	v_mov_b32_dpp v72, v76 row_ror:8 row_mask:0xf bank_mask:0x3
	v_mov_b32_dpp v73, v77 row_ror:8 row_mask:0xf bank_mask:0x3
	v_mov_b32_dpp v74, v78 row_ror:8 row_mask:0xf bank_mask:0x3
	v_mov_b32_dpp v75, v79 row_ror:8 row_mask:0xf bank_mask:0x3
	v_mov_b32_dpp v64, v68 row_ror:8 row_mask:0xf bank_mask:0x3
	v_mov_b32_dpp v65, v69 row_ror:8 row_mask:0xf bank_mask:0x3
	v_mov_b32_dpp v66, v70 row_ror:8 row_mask:0xf bank_mask:0x3
	v_mov_b32_dpp v67, v71 row_ror:8 row_mask:0xf bank_mask:0x3
	v_mov_b32_dpp v76, v158 row_ror:8 row_mask:0xf bank_mask:0xc
	v_mov_b32_dpp v77, v159 row_ror:8 row_mask:0xf bank_mask:0xc
	v_mov_b32_dpp v78, v160 row_ror:8 row_mask:0xf bank_mask:0xc
	v_mov_b32_dpp v79, v161 row_ror:8 row_mask:0xf bank_mask:0xc
	v_mov_b32_dpp v68, v162 row_ror:8 row_mask:0xf bank_mask:0xc
	v_mov_b32_dpp v69, v163 row_ror:8 row_mask:0xf bank_mask:0xc
	v_mov_b32_dpp v70, v164 row_ror:8 row_mask:0xf bank_mask:0xc
	v_mov_b32_dpp v71, v165 row_ror:8 row_mask:0xf bank_mask:0xc
	v_add_u32_e32 v166, 0x60000, v146
	v_add_u32_e32 v167, 0x70000, v146
	v_lshrrev_b32_e32 v168, 1, v166
	v_lshrrev_b32_e32 v169, 1, v167
	s_waitcnt vmcnt(26)
	v_pk_add_f32 v[76:77], v[76:77], v[170:171]
	v_pk_add_f32 v[78:79], v[78:79], v[172:173]
	v_pk_add_f32 v[72:73], v[72:73], v[174:175]
	v_pk_add_f32 v[74:75], v[74:75], v[176:177]
	v_pk_add_f32 v[68:69], v[68:69], v[178:179]
	v_pk_add_f32 v[70:71], v[70:71], v[180:181]
	v_pk_add_f32 v[64:65], v[64:65], v[182:183]
	v_pk_add_f32 v[66:67], v[66:67], v[184:185]
	global_store_dwordx4 v166, v[76:79], s[100:101]
	global_store_dwordx4 v167, v[72:75], s[100:101]
	global_store_dwordx4 v166, v[68:71], s[100:101] offset:512
	global_store_dwordx4 v167, v[64:67], s[100:101] offset:512
	v_cvt_pk_bf16_f32 v158, v76, v77
	v_cvt_pk_bf16_f32 v159, v78, v79
	v_cvt_pk_bf16_f32 v160, v72, v73
	v_cvt_pk_bf16_f32 v161, v74, v75
	v_cvt_pk_bf16_f32 v162, v68, v69
	v_cvt_pk_bf16_f32 v163, v70, v71
	v_cvt_pk_bf16_f32 v164, v64, v65
	v_cvt_pk_bf16_f32 v165, v66, v67
	global_store_dwordx2 v168, v[158:159], s[52:53]
	global_store_dwordx2 v169, v[160:161], s[52:53]
	global_store_dwordx2 v168, v[162:163], s[52:53] offset:256
	global_store_dwordx2 v169, v[164:165], s[52:53] offset:256
	v_mul_f32_e32 v148, v76, v76
	v_mul_f32_e32 v149, v72, v72
	v_fmac_f32_e32 v148, v77, v77
	v_fmac_f32_e32 v149, v73, v73
	v_fmac_f32_e32 v148, v78, v78
	v_fmac_f32_e32 v149, v74, v74
	v_fmac_f32_e32 v148, v79, v79
	v_fmac_f32_e32 v149, v75, v75
	v_fmac_f32_e32 v148, v68, v68
	v_fmac_f32_e32 v149, v64, v64
	v_fmac_f32_e32 v148, v69, v69
	v_fmac_f32_e32 v149, v65, v65
	v_fmac_f32_e32 v148, v70, v70
	v_fmac_f32_e32 v149, v66, v66
	v_fmac_f32_e32 v148, v71, v71
	v_fmac_f32_e32 v149, v67, v67
	s_nop 1
	v_add_f32_dpp v148, v148, v148 row_ror:8 row_mask:0xf bank_mask:0xf
	v_add_f32_dpp v149, v149, v149 row_ror:8 row_mask:0xf bank_mask:0xf
	v_mov_b32_e32 v134, v148
	v_mov_b32_e32 v147, v149
	s_nop 1
	v_permlane16_swap_b32_e32 v148, v134
	v_permlane16_swap_b32_e32 v149, v147
	v_add_f32_e32 v148, v148, v134
	v_add_f32_e32 v149, v149, v147
	v_mov_b32_e32 v134, v148
	v_mov_b32_e32 v147, v149
	s_nop 1
	v_permlane32_swap_b32_e32 v148, v134
	v_permlane32_swap_b32_e32 v149, v147
	v_add_f32_e32 v148, v148, v134
	v_add_f32_e32 v149, v149, v147
	v_cndmask_b32_e32 v148, v148, v149, vcc
	v_lshlrev_b32_e32 v134, 2, v150
	s_mov_b64 exec, s[4:5]
	global_atomic_add_f32 v134, v148, s[50:51] offset:192
	s_mov_b64 exec, -1
	v_add_u32_e32 v166, 0x140000, v146
	v_add_u32_e32 v167, 0x150000, v146
	global_load_dwordx4 v[170:173], v166, s[98:99]
	global_load_dwordx4 v[174:177], v167, s[98:99]
	global_load_dwordx4 v[178:181], v166, s[98:99] offset:512
	global_load_dwordx4 v[182:185], v167, s[98:99] offset:512
	v_mov_b32_e32 v158, v56
	v_mov_b32_e32 v159, v57
	v_mov_b32_e32 v160, v58
	v_mov_b32_e32 v161, v59
	v_mov_b32_e32 v162, v48
	v_mov_b32_e32 v163, v49
	v_mov_b32_e32 v164, v50
	v_mov_b32_e32 v165, v51
	v_mov_b32_dpp v56, v60 row_ror:8 row_mask:0xf bank_mask:0x3
	v_mov_b32_dpp v57, v61 row_ror:8 row_mask:0xf bank_mask:0x3
	v_mov_b32_dpp v58, v62 row_ror:8 row_mask:0xf bank_mask:0x3
	v_mov_b32_dpp v59, v63 row_ror:8 row_mask:0xf bank_mask:0x3
	v_mov_b32_dpp v48, v52 row_ror:8 row_mask:0xf bank_mask:0x3
	v_mov_b32_dpp v49, v53 row_ror:8 row_mask:0xf bank_mask:0x3
	v_mov_b32_dpp v50, v54 row_ror:8 row_mask:0xf bank_mask:0x3
	v_mov_b32_dpp v51, v55 row_ror:8 row_mask:0xf bank_mask:0x3
	v_mov_b32_dpp v60, v158 row_ror:8 row_mask:0xf bank_mask:0xc
	v_mov_b32_dpp v61, v159 row_ror:8 row_mask:0xf bank_mask:0xc
	v_mov_b32_dpp v62, v160 row_ror:8 row_mask:0xf bank_mask:0xc
	v_mov_b32_dpp v63, v161 row_ror:8 row_mask:0xf bank_mask:0xc
	v_mov_b32_dpp v52, v162 row_ror:8 row_mask:0xf bank_mask:0xc
	v_mov_b32_dpp v53, v163 row_ror:8 row_mask:0xf bank_mask:0xc
	v_mov_b32_dpp v54, v164 row_ror:8 row_mask:0xf bank_mask:0xc
	v_mov_b32_dpp v55, v165 row_ror:8 row_mask:0xf bank_mask:0xc
	v_add_u32_e32 v166, 0x100000, v146
	v_add_u32_e32 v167, 0x110000, v146
	v_lshrrev_b32_e32 v168, 1, v166
	v_lshrrev_b32_e32 v169, 1, v167
	s_waitcnt vmcnt(26)
	v_pk_add_f32 v[60:61], v[60:61], v[186:187]
	v_pk_add_f32 v[62:63], v[62:63], v[188:189]
	v_pk_add_f32 v[56:57], v[56:57], v[190:191]
	v_pk_add_f32 v[58:59], v[58:59], v[192:193]
	v_pk_add_f32 v[52:53], v[52:53], v[194:195]
	v_pk_add_f32 v[54:55], v[54:55], v[196:197]
	v_pk_add_f32 v[48:49], v[48:49], v[198:199]
	v_pk_add_f32 v[50:51], v[50:51], v[200:201]
	global_store_dwordx4 v166, v[60:63], s[100:101]
	global_store_dwordx4 v167, v[56:59], s[100:101]
	global_store_dwordx4 v166, v[52:55], s[100:101] offset:512
	global_store_dwordx4 v167, v[48:51], s[100:101] offset:512
	v_cvt_pk_bf16_f32 v158, v60, v61
	v_cvt_pk_bf16_f32 v159, v62, v63
	v_cvt_pk_bf16_f32 v160, v56, v57
	v_cvt_pk_bf16_f32 v161, v58, v59
	v_cvt_pk_bf16_f32 v162, v52, v53
	v_cvt_pk_bf16_f32 v163, v54, v55
	v_cvt_pk_bf16_f32 v164, v48, v49
	v_cvt_pk_bf16_f32 v165, v50, v51
	global_store_dwordx2 v168, v[158:159], s[52:53]
	global_store_dwordx2 v169, v[160:161], s[52:53]
	global_store_dwordx2 v168, v[162:163], s[52:53] offset:256
	global_store_dwordx2 v169, v[164:165], s[52:53] offset:256
	v_mul_f32_e32 v148, v60, v60
	v_mul_f32_e32 v149, v56, v56
	v_fmac_f32_e32 v148, v61, v61
	v_fmac_f32_e32 v149, v57, v57
	v_fmac_f32_e32 v148, v62, v62
	v_fmac_f32_e32 v149, v58, v58
	v_fmac_f32_e32 v148, v63, v63
	v_fmac_f32_e32 v149, v59, v59
	v_fmac_f32_e32 v148, v52, v52
	v_fmac_f32_e32 v149, v48, v48
	v_fmac_f32_e32 v148, v53, v53
	v_fmac_f32_e32 v149, v49, v49
	v_fmac_f32_e32 v148, v54, v54
	v_fmac_f32_e32 v149, v50, v50
	v_fmac_f32_e32 v148, v55, v55
	v_fmac_f32_e32 v149, v51, v51
	s_nop 1
	v_add_f32_dpp v148, v148, v148 row_ror:8 row_mask:0xf bank_mask:0xf
	v_add_f32_dpp v149, v149, v149 row_ror:8 row_mask:0xf bank_mask:0xf
	v_mov_b32_e32 v134, v148
	v_mov_b32_e32 v147, v149
	s_nop 1
	v_permlane16_swap_b32_e32 v148, v134
	v_permlane16_swap_b32_e32 v149, v147
	v_add_f32_e32 v148, v148, v134
	v_add_f32_e32 v149, v149, v147
	v_mov_b32_e32 v134, v148
	v_mov_b32_e32 v147, v149
	s_nop 1
	v_permlane32_swap_b32_e32 v148, v134
	v_permlane32_swap_b32_e32 v149, v147
	v_add_f32_e32 v148, v148, v134
	v_add_f32_e32 v149, v149, v147
	v_cndmask_b32_e32 v148, v148, v149, vcc
	v_lshlrev_b32_e32 v134, 2, v150
	s_mov_b64 exec, s[4:5]
	global_atomic_add_f32 v134, v148, s[50:51] offset:512
	s_mov_b64 exec, -1
	v_add_u32_e32 v166, 0x160000, v146
	v_add_u32_e32 v167, 0x170000, v146
	global_load_dwordx4 v[186:189], v166, s[98:99]
	global_load_dwordx4 v[190:193], v167, s[98:99]
	global_load_dwordx4 v[194:197], v166, s[98:99] offset:512
	global_load_dwordx4 v[198:201], v167, s[98:99] offset:512
	v_mov_b32_e32 v158, v40
	v_mov_b32_e32 v159, v41
	v_mov_b32_e32 v160, v42
	v_mov_b32_e32 v161, v43
	v_mov_b32_e32 v162, v32
	v_mov_b32_e32 v163, v33
	v_mov_b32_e32 v164, v34
	v_mov_b32_e32 v165, v35
	v_mov_b32_dpp v40, v44 row_ror:8 row_mask:0xf bank_mask:0x3
	v_mov_b32_dpp v41, v45 row_ror:8 row_mask:0xf bank_mask:0x3
	v_mov_b32_dpp v42, v46 row_ror:8 row_mask:0xf bank_mask:0x3
	v_mov_b32_dpp v43, v47 row_ror:8 row_mask:0xf bank_mask:0x3
	v_mov_b32_dpp v32, v36 row_ror:8 row_mask:0xf bank_mask:0x3
	v_mov_b32_dpp v33, v37 row_ror:8 row_mask:0xf bank_mask:0x3
	v_mov_b32_dpp v34, v38 row_ror:8 row_mask:0xf bank_mask:0x3
	v_mov_b32_dpp v35, v39 row_ror:8 row_mask:0xf bank_mask:0x3
	v_mov_b32_dpp v44, v158 row_ror:8 row_mask:0xf bank_mask:0xc
	v_mov_b32_dpp v45, v159 row_ror:8 row_mask:0xf bank_mask:0xc
	v_mov_b32_dpp v46, v160 row_ror:8 row_mask:0xf bank_mask:0xc
	v_mov_b32_dpp v47, v161 row_ror:8 row_mask:0xf bank_mask:0xc
	v_mov_b32_dpp v36, v162 row_ror:8 row_mask:0xf bank_mask:0xc
	v_mov_b32_dpp v37, v163 row_ror:8 row_mask:0xf bank_mask:0xc
	v_mov_b32_dpp v38, v164 row_ror:8 row_mask:0xf bank_mask:0xc
	v_mov_b32_dpp v39, v165 row_ror:8 row_mask:0xf bank_mask:0xc
	v_add_u32_e32 v166, 0x120000, v146
	v_add_u32_e32 v167, 0x130000, v146
	v_lshrrev_b32_e32 v168, 1, v166
	v_lshrrev_b32_e32 v169, 1, v167
	s_waitcnt vmcnt(26)
	v_pk_add_f32 v[44:45], v[44:45], v[202:203]
	v_pk_add_f32 v[46:47], v[46:47], v[204:205]
	v_pk_add_f32 v[40:41], v[40:41], v[206:207]
	v_pk_add_f32 v[42:43], v[42:43], v[208:209]
	v_pk_add_f32 v[36:37], v[36:37], v[210:211]
	v_pk_add_f32 v[38:39], v[38:39], v[212:213]
	v_pk_add_f32 v[32:33], v[32:33], v[214:215]
	v_pk_add_f32 v[34:35], v[34:35], v[216:217]
	global_store_dwordx4 v166, v[44:47], s[100:101]
	global_store_dwordx4 v167, v[40:43], s[100:101]
	global_store_dwordx4 v166, v[36:39], s[100:101] offset:512
	global_store_dwordx4 v167, v[32:35], s[100:101] offset:512
	v_cvt_pk_bf16_f32 v158, v44, v45
	v_cvt_pk_bf16_f32 v159, v46, v47
	v_cvt_pk_bf16_f32 v160, v40, v41
	v_cvt_pk_bf16_f32 v161, v42, v43
	v_cvt_pk_bf16_f32 v162, v36, v37
	v_cvt_pk_bf16_f32 v163, v38, v39
	v_cvt_pk_bf16_f32 v164, v32, v33
	v_cvt_pk_bf16_f32 v165, v34, v35
	global_store_dwordx2 v168, v[158:159], s[52:53]
	global_store_dwordx2 v169, v[160:161], s[52:53]
	global_store_dwordx2 v168, v[162:163], s[52:53] offset:256
	global_store_dwordx2 v169, v[164:165], s[52:53] offset:256
	v_mul_f32_e32 v148, v44, v44
	v_mul_f32_e32 v149, v40, v40
	v_fmac_f32_e32 v148, v45, v45
	v_fmac_f32_e32 v149, v41, v41
	v_fmac_f32_e32 v148, v46, v46
	v_fmac_f32_e32 v149, v42, v42
	v_fmac_f32_e32 v148, v47, v47
	v_fmac_f32_e32 v149, v43, v43
	v_fmac_f32_e32 v148, v36, v36
	v_fmac_f32_e32 v149, v32, v32
	v_fmac_f32_e32 v148, v37, v37
	v_fmac_f32_e32 v149, v33, v33
	v_fmac_f32_e32 v148, v38, v38
	v_fmac_f32_e32 v149, v34, v34
	v_fmac_f32_e32 v148, v39, v39
	v_fmac_f32_e32 v149, v35, v35
	s_nop 1
	v_add_f32_dpp v148, v148, v148 row_ror:8 row_mask:0xf bank_mask:0xf
	v_add_f32_dpp v149, v149, v149 row_ror:8 row_mask:0xf bank_mask:0xf
	v_mov_b32_e32 v134, v148
	v_mov_b32_e32 v147, v149
	s_nop 1
	v_permlane16_swap_b32_e32 v148, v134
	v_permlane16_swap_b32_e32 v149, v147
	v_add_f32_e32 v148, v148, v134
	v_add_f32_e32 v149, v149, v147
	v_mov_b32_e32 v134, v148
	v_mov_b32_e32 v147, v149
	s_nop 1
	v_permlane32_swap_b32_e32 v148, v134
	v_permlane32_swap_b32_e32 v149, v147
	v_add_f32_e32 v148, v148, v134
	v_add_f32_e32 v149, v149, v147
	v_cndmask_b32_e32 v148, v148, v149, vcc
	v_lshlrev_b32_e32 v134, 2, v150
	s_mov_b64 exec, s[4:5]
	global_atomic_add_f32 v134, v148, s[50:51] offset:576
	s_mov_b64 exec, -1
	v_mov_b32_e32 v158, v24
	v_mov_b32_e32 v159, v25
	v_mov_b32_e32 v160, v26
	v_mov_b32_e32 v161, v27
	v_mov_b32_e32 v162, v16
	v_mov_b32_e32 v163, v17
	v_mov_b32_e32 v164, v18
	v_mov_b32_e32 v165, v19
	v_mov_b32_dpp v24, v28 row_ror:8 row_mask:0xf bank_mask:0x3
	v_mov_b32_dpp v25, v29 row_ror:8 row_mask:0xf bank_mask:0x3
	v_mov_b32_dpp v26, v30 row_ror:8 row_mask:0xf bank_mask:0x3
	v_mov_b32_dpp v27, v31 row_ror:8 row_mask:0xf bank_mask:0x3
	v_mov_b32_dpp v16, v20 row_ror:8 row_mask:0xf bank_mask:0x3
	v_mov_b32_dpp v17, v21 row_ror:8 row_mask:0xf bank_mask:0x3
	v_mov_b32_dpp v18, v22 row_ror:8 row_mask:0xf bank_mask:0x3
	v_mov_b32_dpp v19, v23 row_ror:8 row_mask:0xf bank_mask:0x3
	v_mov_b32_dpp v28, v158 row_ror:8 row_mask:0xf bank_mask:0xc
	v_mov_b32_dpp v29, v159 row_ror:8 row_mask:0xf bank_mask:0xc
	v_mov_b32_dpp v30, v160 row_ror:8 row_mask:0xf bank_mask:0xc
	v_mov_b32_dpp v31, v161 row_ror:8 row_mask:0xf bank_mask:0xc
	v_mov_b32_dpp v20, v162 row_ror:8 row_mask:0xf bank_mask:0xc
	v_mov_b32_dpp v21, v163 row_ror:8 row_mask:0xf bank_mask:0xc
	v_mov_b32_dpp v22, v164 row_ror:8 row_mask:0xf bank_mask:0xc
	v_mov_b32_dpp v23, v165 row_ror:8 row_mask:0xf bank_mask:0xc
	v_add_u32_e32 v166, 0x140000, v146
	v_add_u32_e32 v167, 0x150000, v146
	v_lshrrev_b32_e32 v168, 1, v166
	v_lshrrev_b32_e32 v169, 1, v167
	s_waitcnt vmcnt(22)
	v_pk_add_f32 v[28:29], v[28:29], v[170:171]
	v_pk_add_f32 v[30:31], v[30:31], v[172:173]
	v_pk_add_f32 v[24:25], v[24:25], v[174:175]
	v_pk_add_f32 v[26:27], v[26:27], v[176:177]
	v_pk_add_f32 v[20:21], v[20:21], v[178:179]
	v_pk_add_f32 v[22:23], v[22:23], v[180:181]
	v_pk_add_f32 v[16:17], v[16:17], v[182:183]
	v_pk_add_f32 v[18:19], v[18:19], v[184:185]
	global_store_dwordx4 v166, v[28:31], s[100:101]
	global_store_dwordx4 v167, v[24:27], s[100:101]
	global_store_dwordx4 v166, v[20:23], s[100:101] offset:512
	global_store_dwordx4 v167, v[16:19], s[100:101] offset:512
	v_cvt_pk_bf16_f32 v158, v28, v29
	v_cvt_pk_bf16_f32 v159, v30, v31
	v_cvt_pk_bf16_f32 v160, v24, v25
	v_cvt_pk_bf16_f32 v161, v26, v27
	v_cvt_pk_bf16_f32 v162, v20, v21
	v_cvt_pk_bf16_f32 v163, v22, v23
	v_cvt_pk_bf16_f32 v164, v16, v17
	v_cvt_pk_bf16_f32 v165, v18, v19
	global_store_dwordx2 v168, v[158:159], s[52:53]
	global_store_dwordx2 v169, v[160:161], s[52:53]
	global_store_dwordx2 v168, v[162:163], s[52:53] offset:256
	global_store_dwordx2 v169, v[164:165], s[52:53] offset:256
	v_mul_f32_e32 v148, v28, v28
	v_mul_f32_e32 v149, v24, v24
	v_fmac_f32_e32 v148, v29, v29
	v_fmac_f32_e32 v149, v25, v25
	v_fmac_f32_e32 v148, v30, v30
	v_fmac_f32_e32 v149, v26, v26
	v_fmac_f32_e32 v148, v31, v31
	v_fmac_f32_e32 v149, v27, v27
	v_fmac_f32_e32 v148, v20, v20
	v_fmac_f32_e32 v149, v16, v16
	v_fmac_f32_e32 v148, v21, v21
	v_fmac_f32_e32 v149, v17, v17
	v_fmac_f32_e32 v148, v22, v22
	v_fmac_f32_e32 v149, v18, v18
	v_fmac_f32_e32 v148, v23, v23
	v_fmac_f32_e32 v149, v19, v19
	s_nop 1
	v_add_f32_dpp v148, v148, v148 row_ror:8 row_mask:0xf bank_mask:0xf
	v_add_f32_dpp v149, v149, v149 row_ror:8 row_mask:0xf bank_mask:0xf
	v_mov_b32_e32 v134, v148
	v_mov_b32_e32 v147, v149
	s_nop 1
	v_permlane16_swap_b32_e32 v148, v134
	v_permlane16_swap_b32_e32 v149, v147
	v_add_f32_e32 v148, v148, v134
	v_add_f32_e32 v149, v149, v147
	v_mov_b32_e32 v134, v148
	v_mov_b32_e32 v147, v149
	s_nop 1
	v_permlane32_swap_b32_e32 v148, v134
	v_permlane32_swap_b32_e32 v149, v147
	v_add_f32_e32 v148, v148, v134
	v_add_f32_e32 v149, v149, v147
	v_cndmask_b32_e32 v148, v148, v149, vcc
	v_lshlrev_b32_e32 v134, 2, v150
	s_mov_b64 exec, s[4:5]
	global_atomic_add_f32 v134, v148, s[50:51] offset:640
	s_mov_b64 exec, -1
	v_mov_b32_e32 v158, v8
	v_mov_b32_e32 v159, v9
	v_mov_b32_e32 v160, v10
	v_mov_b32_e32 v161, v11
	v_mov_b32_e32 v162, v0
	v_mov_b32_e32 v163, v1
	v_mov_b32_e32 v164, v2
	v_mov_b32_e32 v165, v3
	v_mov_b32_dpp v8, v12 row_ror:8 row_mask:0xf bank_mask:0x3
	v_mov_b32_dpp v9, v13 row_ror:8 row_mask:0xf bank_mask:0x3
	v_mov_b32_dpp v10, v14 row_ror:8 row_mask:0xf bank_mask:0x3
	v_mov_b32_dpp v11, v15 row_ror:8 row_mask:0xf bank_mask:0x3
	v_mov_b32_dpp v0, v4 row_ror:8 row_mask:0xf bank_mask:0x3
	v_mov_b32_dpp v1, v5 row_ror:8 row_mask:0xf bank_mask:0x3
	v_mov_b32_dpp v2, v6 row_ror:8 row_mask:0xf bank_mask:0x3
	v_mov_b32_dpp v3, v7 row_ror:8 row_mask:0xf bank_mask:0x3
	v_mov_b32_dpp v12, v158 row_ror:8 row_mask:0xf bank_mask:0xc
	v_mov_b32_dpp v13, v159 row_ror:8 row_mask:0xf bank_mask:0xc
	v_mov_b32_dpp v14, v160 row_ror:8 row_mask:0xf bank_mask:0xc
	v_mov_b32_dpp v15, v161 row_ror:8 row_mask:0xf bank_mask:0xc
	v_mov_b32_dpp v4, v162 row_ror:8 row_mask:0xf bank_mask:0xc
	v_mov_b32_dpp v5, v163 row_ror:8 row_mask:0xf bank_mask:0xc
	v_mov_b32_dpp v6, v164 row_ror:8 row_mask:0xf bank_mask:0xc
	v_mov_b32_dpp v7, v165 row_ror:8 row_mask:0xf bank_mask:0xc
	v_add_u32_e32 v166, 0x160000, v146
	v_add_u32_e32 v167, 0x170000, v146
	v_lshrrev_b32_e32 v168, 1, v166
	v_lshrrev_b32_e32 v169, 1, v167
	s_waitcnt vmcnt(18)
	v_pk_add_f32 v[12:13], v[12:13], v[186:187]
	v_pk_add_f32 v[14:15], v[14:15], v[188:189]
	v_pk_add_f32 v[8:9], v[8:9], v[190:191]
	v_pk_add_f32 v[10:11], v[10:11], v[192:193]
	v_pk_add_f32 v[4:5], v[4:5], v[194:195]
	v_pk_add_f32 v[6:7], v[6:7], v[196:197]
	v_pk_add_f32 v[0:1], v[0:1], v[198:199]
	v_pk_add_f32 v[2:3], v[2:3], v[200:201]
	global_store_dwordx4 v166, v[12:15], s[100:101]
	global_store_dwordx4 v167, v[8:11], s[100:101]
	global_store_dwordx4 v166, v[4:7], s[100:101] offset:512
	global_store_dwordx4 v167, v[0:3], s[100:101] offset:512
	v_cvt_pk_bf16_f32 v158, v12, v13
	v_cvt_pk_bf16_f32 v159, v14, v15
	v_cvt_pk_bf16_f32 v160, v8, v9
	v_cvt_pk_bf16_f32 v161, v10, v11
	v_cvt_pk_bf16_f32 v162, v4, v5
	v_cvt_pk_bf16_f32 v163, v6, v7
	v_cvt_pk_bf16_f32 v164, v0, v1
	v_cvt_pk_bf16_f32 v165, v2, v3
	global_store_dwordx2 v168, v[158:159], s[52:53]
	global_store_dwordx2 v169, v[160:161], s[52:53]
	global_store_dwordx2 v168, v[162:163], s[52:53] offset:256
	global_store_dwordx2 v169, v[164:165], s[52:53] offset:256
	v_mul_f32_e32 v148, v12, v12
	v_mul_f32_e32 v149, v8, v8
	v_fmac_f32_e32 v148, v13, v13
	v_fmac_f32_e32 v149, v9, v9
	v_fmac_f32_e32 v148, v14, v14
	v_fmac_f32_e32 v149, v10, v10
	v_fmac_f32_e32 v148, v15, v15
	v_fmac_f32_e32 v149, v11, v11
	v_fmac_f32_e32 v148, v4, v4
	v_fmac_f32_e32 v149, v0, v0
	v_fmac_f32_e32 v148, v5, v5
	v_fmac_f32_e32 v149, v1, v1
	v_fmac_f32_e32 v148, v6, v6
	v_fmac_f32_e32 v149, v2, v2
	v_fmac_f32_e32 v148, v7, v7
	v_fmac_f32_e32 v149, v3, v3
	s_nop 1
	v_add_f32_dpp v148, v148, v148 row_ror:8 row_mask:0xf bank_mask:0xf
	v_add_f32_dpp v149, v149, v149 row_ror:8 row_mask:0xf bank_mask:0xf
	v_mov_b32_e32 v134, v148
	v_mov_b32_e32 v147, v149
	s_nop 1
	v_permlane16_swap_b32_e32 v148, v134
	v_permlane16_swap_b32_e32 v149, v147
	v_add_f32_e32 v148, v148, v134
	v_add_f32_e32 v149, v149, v147
	v_mov_b32_e32 v134, v148
	v_mov_b32_e32 v147, v149
	s_nop 1
	v_permlane32_swap_b32_e32 v148, v134
	v_permlane32_swap_b32_e32 v149, v147
	v_add_f32_e32 v148, v148, v134
	v_add_f32_e32 v149, v149, v147
	v_cndmask_b32_e32 v148, v148, v149, vcc
	v_lshlrev_b32_e32 v134, 2, v150
	s_mov_b64 exec, s[4:5]
	global_atomic_add_f32 v134, v148, s[50:51] offset:704
	s_mov_b64 exec, -1
	s_branch .LBB0_1142
.Lepo_tail:
	v_mov_b32_e32 v166, v146
	v_add_u32_e32 v167, 0x10000, v146
	global_load_dwordx4 v[170:173], v166, s[98:99]
	global_load_dwordx4 v[174:177], v167, s[98:99]
	global_load_dwordx4 v[178:181], v166, s[98:99] offset:512
	global_load_dwordx4 v[182:185], v167, s[98:99] offset:512
	v_add_u32_e32 v166, 0x20000, v146
	v_add_u32_e32 v167, 0x30000, v146
	global_load_dwordx4 v[186:189], v166, s[98:99]
	global_load_dwordx4 v[190:193], v167, s[98:99]
	global_load_dwordx4 v[194:197], v166, s[98:99] offset:512
	global_load_dwordx4 v[198:201], v167, s[98:99] offset:512
	v_add_u32_e32 v166, 0x40000, v146
	v_add_u32_e32 v167, 0x50000, v146
	global_load_dwordx4 v[202:205], v166, s[98:99]
	global_load_dwordx4 v[206:209], v167, s[98:99]
	global_load_dwordx4 v[210:213], v166, s[98:99] offset:512
	global_load_dwordx4 v[214:217], v167, s[98:99] offset:512
	v_mov_b32_e32 v158, v120
	v_mov_b32_e32 v159, v121
	v_mov_b32_e32 v160, v122
	v_mov_b32_e32 v161, v123
	v_mov_b32_e32 v162, v112
	v_mov_b32_e32 v163, v113
	v_mov_b32_e32 v164, v114
	v_mov_b32_e32 v165, v115
	v_mov_b32_dpp v120, v124 row_ror:8 row_mask:0xf bank_mask:0x3
	v_mov_b32_dpp v121, v125 row_ror:8 row_mask:0xf bank_mask:0x3
	v_mov_b32_dpp v122, v126 row_ror:8 row_mask:0xf bank_mask:0x3
	v_mov_b32_dpp v123, v127 row_ror:8 row_mask:0xf bank_mask:0x3
	v_mov_b32_dpp v112, v116 row_ror:8 row_mask:0xf bank_mask:0x3
	v_mov_b32_dpp v113, v117 row_ror:8 row_mask:0xf bank_mask:0x3
	v_mov_b32_dpp v114, v118 row_ror:8 row_mask:0xf bank_mask:0x3
	v_mov_b32_dpp v115, v119 row_ror:8 row_mask:0xf bank_mask:0x3
	v_mov_b32_dpp v124, v158 row_ror:8 row_mask:0xf bank_mask:0xc
	v_mov_b32_dpp v125, v159 row_ror:8 row_mask:0xf bank_mask:0xc
	v_mov_b32_dpp v126, v160 row_ror:8 row_mask:0xf bank_mask:0xc
	v_mov_b32_dpp v127, v161 row_ror:8 row_mask:0xf bank_mask:0xc
	v_mov_b32_dpp v116, v162 row_ror:8 row_mask:0xf bank_mask:0xc
	v_mov_b32_dpp v117, v163 row_ror:8 row_mask:0xf bank_mask:0xc
	v_mov_b32_dpp v118, v164 row_ror:8 row_mask:0xf bank_mask:0xc
	v_mov_b32_dpp v119, v165 row_ror:8 row_mask:0xf bank_mask:0xc
	v_mov_b32_e32 v166, v146
	v_add_u32_e32 v167, 0x10000, v146
	v_lshrrev_b32_e32 v168, 1, v166
	v_lshrrev_b32_e32 v169, 1, v167
	s_waitcnt vmcnt(8)
	v_pk_add_f32 v[124:125], v[124:125], v[170:171]
	v_pk_add_f32 v[126:127], v[126:127], v[172:173]
	v_pk_add_f32 v[120:121], v[120:121], v[174:175]
	v_pk_add_f32 v[122:123], v[122:123], v[176:177]
	v_pk_add_f32 v[116:117], v[116:117], v[178:179]
	v_pk_add_f32 v[118:119], v[118:119], v[180:181]
	v_pk_add_f32 v[112:113], v[112:113], v[182:183]
	v_pk_add_f32 v[114:115], v[114:115], v[184:185]
	global_store_dwordx4 v166, v[124:127], s[100:101]
	global_store_dwordx4 v167, v[120:123], s[100:101]
	global_store_dwordx4 v166, v[116:119], s[100:101] offset:512
	global_store_dwordx4 v167, v[112:115], s[100:101] offset:512
	v_cvt_pk_bf16_f32 v158, v124, v125
	v_cvt_pk_bf16_f32 v159, v126, v127
	v_cvt_pk_bf16_f32 v160, v120, v121
	v_cvt_pk_bf16_f32 v161, v122, v123
	v_cvt_pk_bf16_f32 v162, v116, v117
	v_cvt_pk_bf16_f32 v163, v118, v119
	v_cvt_pk_bf16_f32 v164, v112, v113
	v_cvt_pk_bf16_f32 v165, v114, v115
	global_store_dwordx2 v168, v[158:159], s[52:53]
	global_store_dwordx2 v169, v[160:161], s[52:53]
	global_store_dwordx2 v168, v[162:163], s[52:53] offset:256
	global_store_dwordx2 v169, v[164:165], s[52:53] offset:256
	v_mul_f32_e32 v148, v124, v124
	v_mul_f32_e32 v149, v120, v120
	v_fmac_f32_e32 v148, v125, v125
	v_fmac_f32_e32 v149, v121, v121
	v_fmac_f32_e32 v148, v126, v126
	v_fmac_f32_e32 v149, v122, v122
	v_fmac_f32_e32 v148, v127, v127
	v_fmac_f32_e32 v149, v123, v123
	v_fmac_f32_e32 v148, v116, v116
	v_fmac_f32_e32 v149, v112, v112
	v_fmac_f32_e32 v148, v117, v117
	v_fmac_f32_e32 v149, v113, v113
	v_fmac_f32_e32 v148, v118, v118
	v_fmac_f32_e32 v149, v114, v114
	v_fmac_f32_e32 v148, v119, v119
	v_fmac_f32_e32 v149, v115, v115
	s_nop 1
	v_add_f32_dpp v148, v148, v148 row_ror:8 row_mask:0xf bank_mask:0xf
	v_add_f32_dpp v149, v149, v149 row_ror:8 row_mask:0xf bank_mask:0xf
	v_mov_b32_e32 v134, v148
	v_mov_b32_e32 v147, v149
	s_nop 1
	v_permlane16_swap_b32_e32 v148, v134
	v_permlane16_swap_b32_e32 v149, v147
	v_add_f32_e32 v148, v148, v134
	v_add_f32_e32 v149, v149, v147
	v_mov_b32_e32 v134, v148
	v_mov_b32_e32 v147, v149
	s_nop 1
	v_permlane32_swap_b32_e32 v148, v134
	v_permlane32_swap_b32_e32 v149, v147
	v_add_f32_e32 v148, v148, v134
	v_add_f32_e32 v149, v149, v147
	v_cndmask_b32_e32 v148, v148, v149, vcc
	v_lshlrev_b32_e32 v134, 2, v150
	s_mov_b64 exec, s[4:5]
	global_atomic_add_f32 v134, v148, s[50:51]
	s_mov_b64 exec, -1
	v_add_u32_e32 v166, 0x60000, v146
	v_add_u32_e32 v167, 0x70000, v146
	global_load_dwordx4 v[170:173], v166, s[98:99]
	global_load_dwordx4 v[174:177], v167, s[98:99]
	global_load_dwordx4 v[178:181], v166, s[98:99] offset:512
	global_load_dwordx4 v[182:185], v167, s[98:99] offset:512
	v_mov_b32_e32 v158, v104
	v_mov_b32_e32 v159, v105
	v_mov_b32_e32 v160, v106
	v_mov_b32_e32 v161, v107
	v_mov_b32_e32 v162, v96
	v_mov_b32_e32 v163, v97
	v_mov_b32_e32 v164, v98
	v_mov_b32_e32 v165, v99
	v_mov_b32_dpp v104, v108 row_ror:8 row_mask:0xf bank_mask:0x3
	v_mov_b32_dpp v105, v109 row_ror:8 row_mask:0xf bank_mask:0x3
	v_mov_b32_dpp v106, v110 row_ror:8 row_mask:0xf bank_mask:0x3
	v_mov_b32_dpp v107, v111 row_ror:8 row_mask:0xf bank_mask:0x3
	v_mov_b32_dpp v96, v100 row_ror:8 row_mask:0xf bank_mask:0x3
	v_mov_b32_dpp v97, v101 row_ror:8 row_mask:0xf bank_mask:0x3
	v_mov_b32_dpp v98, v102 row_ror:8 row_mask:0xf bank_mask:0x3
	v_mov_b32_dpp v99, v103 row_ror:8 row_mask:0xf bank_mask:0x3
	v_mov_b32_dpp v108, v158 row_ror:8 row_mask:0xf bank_mask:0xc
	v_mov_b32_dpp v109, v159 row_ror:8 row_mask:0xf bank_mask:0xc
	v_mov_b32_dpp v110, v160 row_ror:8 row_mask:0xf bank_mask:0xc
	v_mov_b32_dpp v111, v161 row_ror:8 row_mask:0xf bank_mask:0xc
	v_mov_b32_dpp v100, v162 row_ror:8 row_mask:0xf bank_mask:0xc
	v_mov_b32_dpp v101, v163 row_ror:8 row_mask:0xf bank_mask:0xc
	v_mov_b32_dpp v102, v164 row_ror:8 row_mask:0xf bank_mask:0xc
	v_mov_b32_dpp v103, v165 row_ror:8 row_mask:0xf bank_mask:0xc
	v_add_u32_e32 v166, 0x20000, v146
	v_add_u32_e32 v167, 0x30000, v146
	v_lshrrev_b32_e32 v168, 1, v166
	v_lshrrev_b32_e32 v169, 1, v167
	s_waitcnt vmcnt(17)
	v_pk_add_f32 v[108:109], v[108:109], v[186:187]
	v_pk_add_f32 v[110:111], v[110:111], v[188:189]
	v_pk_add_f32 v[104:105], v[104:105], v[190:191]
	v_pk_add_f32 v[106:107], v[106:107], v[192:193]
	v_pk_add_f32 v[100:101], v[100:101], v[194:195]
	v_pk_add_f32 v[102:103], v[102:103], v[196:197]
	v_pk_add_f32 v[96:97], v[96:97], v[198:199]
	v_pk_add_f32 v[98:99], v[98:99], v[200:201]
	global_store_dwordx4 v166, v[108:111], s[100:101]
	global_store_dwordx4 v167, v[104:107], s[100:101]
	global_store_dwordx4 v166, v[100:103], s[100:101] offset:512
	global_store_dwordx4 v167, v[96:99], s[100:101] offset:512
	v_cvt_pk_bf16_f32 v158, v108, v109
	v_cvt_pk_bf16_f32 v159, v110, v111
	v_cvt_pk_bf16_f32 v160, v104, v105
	v_cvt_pk_bf16_f32 v161, v106, v107
	v_cvt_pk_bf16_f32 v162, v100, v101
	v_cvt_pk_bf16_f32 v163, v102, v103
	v_cvt_pk_bf16_f32 v164, v96, v97
	v_cvt_pk_bf16_f32 v165, v98, v99
	global_store_dwordx2 v168, v[158:159], s[52:53]
	global_store_dwordx2 v169, v[160:161], s[52:53]
	global_store_dwordx2 v168, v[162:163], s[52:53] offset:256
	global_store_dwordx2 v169, v[164:165], s[52:53] offset:256
	v_mul_f32_e32 v148, v108, v108
	v_mul_f32_e32 v149, v104, v104
	v_fmac_f32_e32 v148, v109, v109
	v_fmac_f32_e32 v149, v105, v105
	v_fmac_f32_e32 v148, v110, v110
	v_fmac_f32_e32 v149, v106, v106
	v_fmac_f32_e32 v148, v111, v111
	v_fmac_f32_e32 v149, v107, v107
	v_fmac_f32_e32 v148, v100, v100
	v_fmac_f32_e32 v149, v96, v96
	v_fmac_f32_e32 v148, v101, v101
	v_fmac_f32_e32 v149, v97, v97
	v_fmac_f32_e32 v148, v102, v102
	v_fmac_f32_e32 v149, v98, v98
	v_fmac_f32_e32 v148, v103, v103
	v_fmac_f32_e32 v149, v99, v99
	s_nop 1
	v_add_f32_dpp v148, v148, v148 row_ror:8 row_mask:0xf bank_mask:0xf
	v_add_f32_dpp v149, v149, v149 row_ror:8 row_mask:0xf bank_mask:0xf
	v_mov_b32_e32 v134, v148
	v_mov_b32_e32 v147, v149
	s_nop 1
	v_permlane16_swap_b32_e32 v148, v134
	v_permlane16_swap_b32_e32 v149, v147
	v_add_f32_e32 v148, v148, v134
	v_add_f32_e32 v149, v149, v147
	v_mov_b32_e32 v134, v148
	v_mov_b32_e32 v147, v149
	s_nop 1
	v_permlane32_swap_b32_e32 v148, v134
	v_permlane32_swap_b32_e32 v149, v147
	v_add_f32_e32 v148, v148, v134
	v_add_f32_e32 v149, v149, v147
	v_cndmask_b32_e32 v148, v148, v149, vcc
	v_lshlrev_b32_e32 v134, 2, v150
	s_mov_b64 exec, s[4:5]
	global_atomic_add_f32 v134, v148, s[50:51] offset:64
	s_mov_b64 exec, -1
	v_mov_b32_e32 v158, v88
	v_mov_b32_e32 v159, v89
	v_mov_b32_e32 v160, v90
	v_mov_b32_e32 v161, v91
	v_mov_b32_e32 v162, v80
	v_mov_b32_e32 v163, v81
	v_mov_b32_e32 v164, v82
	v_mov_b32_e32 v165, v83
	v_mov_b32_dpp v88, v92 row_ror:8 row_mask:0xf bank_mask:0x3
	v_mov_b32_dpp v89, v93 row_ror:8 row_mask:0xf bank_mask:0x3
	v_mov_b32_dpp v90, v94 row_ror:8 row_mask:0xf bank_mask:0x3
	v_mov_b32_dpp v91, v95 row_ror:8 row_mask:0xf bank_mask:0x3
	v_mov_b32_dpp v80, v84 row_ror:8 row_mask:0xf bank_mask:0x3
	v_mov_b32_dpp v81, v85 row_ror:8 row_mask:0xf bank_mask:0x3
	v_mov_b32_dpp v82, v86 row_ror:8 row_mask:0xf bank_mask:0x3
	v_mov_b32_dpp v83, v87 row_ror:8 row_mask:0xf bank_mask:0x3
	v_mov_b32_dpp v92, v158 row_ror:8 row_mask:0xf bank_mask:0xc
	v_mov_b32_dpp v93, v159 row_ror:8 row_mask:0xf bank_mask:0xc
	v_mov_b32_dpp v94, v160 row_ror:8 row_mask:0xf bank_mask:0xc
	v_mov_b32_dpp v95, v161 row_ror:8 row_mask:0xf bank_mask:0xc
	v_mov_b32_dpp v84, v162 row_ror:8 row_mask:0xf bank_mask:0xc
	v_mov_b32_dpp v85, v163 row_ror:8 row_mask:0xf bank_mask:0xc
	v_mov_b32_dpp v86, v164 row_ror:8 row_mask:0xf bank_mask:0xc
	v_mov_b32_dpp v87, v165 row_ror:8 row_mask:0xf bank_mask:0xc
	v_add_u32_e32 v166, 0x40000, v146
	v_add_u32_e32 v167, 0x50000, v146
	v_lshrrev_b32_e32 v168, 1, v166
	v_lshrrev_b32_e32 v169, 1, v167
	s_waitcnt vmcnt(22)
	v_pk_add_f32 v[92:93], v[92:93], v[202:203]
	v_pk_add_f32 v[94:95], v[94:95], v[204:205]
	v_pk_add_f32 v[88:89], v[88:89], v[206:207]
	v_pk_add_f32 v[90:91], v[90:91], v[208:209]
	v_pk_add_f32 v[84:85], v[84:85], v[210:211]
	v_pk_add_f32 v[86:87], v[86:87], v[212:213]
	v_pk_add_f32 v[80:81], v[80:81], v[214:215]
	v_pk_add_f32 v[82:83], v[82:83], v[216:217]
	global_store_dwordx4 v166, v[92:95], s[100:101]
	global_store_dwordx4 v167, v[88:91], s[100:101]
	global_store_dwordx4 v166, v[84:87], s[100:101] offset:512
	global_store_dwordx4 v167, v[80:83], s[100:101] offset:512
	v_cvt_pk_bf16_f32 v158, v92, v93
	v_cvt_pk_bf16_f32 v159, v94, v95
	v_cvt_pk_bf16_f32 v160, v88, v89
	v_cvt_pk_bf16_f32 v161, v90, v91
	v_cvt_pk_bf16_f32 v162, v84, v85
	v_cvt_pk_bf16_f32 v163, v86, v87
	v_cvt_pk_bf16_f32 v164, v80, v81
	v_cvt_pk_bf16_f32 v165, v82, v83
	global_store_dwordx2 v168, v[158:159], s[52:53]
	global_store_dwordx2 v169, v[160:161], s[52:53]
	global_store_dwordx2 v168, v[162:163], s[52:53] offset:256
	global_store_dwordx2 v169, v[164:165], s[52:53] offset:256
	v_mul_f32_e32 v148, v92, v92
	v_mul_f32_e32 v149, v88, v88
	v_fmac_f32_e32 v148, v93, v93
	v_fmac_f32_e32 v149, v89, v89
	v_fmac_f32_e32 v148, v94, v94
	v_fmac_f32_e32 v149, v90, v90
	v_fmac_f32_e32 v148, v95, v95
	v_fmac_f32_e32 v149, v91, v91
	v_fmac_f32_e32 v148, v84, v84
	v_fmac_f32_e32 v149, v80, v80
	v_fmac_f32_e32 v148, v85, v85
	v_fmac_f32_e32 v149, v81, v81
	v_fmac_f32_e32 v148, v86, v86
	v_fmac_f32_e32 v149, v82, v82
	v_fmac_f32_e32 v148, v87, v87
	v_fmac_f32_e32 v149, v83, v83
	s_nop 1
	v_add_f32_dpp v148, v148, v148 row_ror:8 row_mask:0xf bank_mask:0xf
	v_add_f32_dpp v149, v149, v149 row_ror:8 row_mask:0xf bank_mask:0xf
	v_mov_b32_e32 v134, v148
	v_mov_b32_e32 v147, v149
	s_nop 1
	v_permlane16_swap_b32_e32 v148, v134
	v_permlane16_swap_b32_e32 v149, v147
	v_add_f32_e32 v148, v148, v134
	v_add_f32_e32 v149, v149, v147
	v_mov_b32_e32 v134, v148
	v_mov_b32_e32 v147, v149
	s_nop 1
	v_permlane32_swap_b32_e32 v148, v134
	v_permlane32_swap_b32_e32 v149, v147
	v_add_f32_e32 v148, v148, v134
	v_add_f32_e32 v149, v149, v147
	v_cndmask_b32_e32 v148, v148, v149, vcc
	v_lshlrev_b32_e32 v134, 2, v150
	s_mov_b64 exec, s[4:5]
	global_atomic_add_f32 v134, v148, s[50:51] offset:128
	s_mov_b64 exec, -1
	v_mov_b32_e32 v158, v72
	v_mov_b32_e32 v159, v73
	v_mov_b32_e32 v160, v74
	v_mov_b32_e32 v161, v75
	v_mov_b32_e32 v162, v64
	v_mov_b32_e32 v163, v65
	v_mov_b32_e32 v164, v66
	v_mov_b32_e32 v165, v67
	v_mov_b32_dpp v72, v76 row_ror:8 row_mask:0xf bank_mask:0x3
	v_mov_b32_dpp v73, v77 row_ror:8 row_mask:0xf bank_mask:0x3
	v_mov_b32_dpp v74, v78 row_ror:8 row_mask:0xf bank_mask:0x3
	v_mov_b32_dpp v75, v79 row_ror:8 row_mask:0xf bank_mask:0x3
	v_mov_b32_dpp v64, v68 row_ror:8 row_mask:0xf bank_mask:0x3
	v_mov_b32_dpp v65, v69 row_ror:8 row_mask:0xf bank_mask:0x3
	v_mov_b32_dpp v66, v70 row_ror:8 row_mask:0xf bank_mask:0x3
	v_mov_b32_dpp v67, v71 row_ror:8 row_mask:0xf bank_mask:0x3
	v_mov_b32_dpp v76, v158 row_ror:8 row_mask:0xf bank_mask:0xc
	v_mov_b32_dpp v77, v159 row_ror:8 row_mask:0xf bank_mask:0xc
	v_mov_b32_dpp v78, v160 row_ror:8 row_mask:0xf bank_mask:0xc
	v_mov_b32_dpp v79, v161 row_ror:8 row_mask:0xf bank_mask:0xc
	v_mov_b32_dpp v68, v162 row_ror:8 row_mask:0xf bank_mask:0xc
	v_mov_b32_dpp v69, v163 row_ror:8 row_mask:0xf bank_mask:0xc
	v_mov_b32_dpp v70, v164 row_ror:8 row_mask:0xf bank_mask:0xc
	v_mov_b32_dpp v71, v165 row_ror:8 row_mask:0xf bank_mask:0xc
	v_add_u32_e32 v166, 0x60000, v146
	v_add_u32_e32 v167, 0x70000, v146
	v_lshrrev_b32_e32 v168, 1, v166
	v_lshrrev_b32_e32 v169, 1, v167
	s_waitcnt vmcnt(18)
	v_pk_add_f32 v[76:77], v[76:77], v[170:171]
	v_pk_add_f32 v[78:79], v[78:79], v[172:173]
	v_pk_add_f32 v[72:73], v[72:73], v[174:175]
	v_pk_add_f32 v[74:75], v[74:75], v[176:177]
	v_pk_add_f32 v[68:69], v[68:69], v[178:179]
	v_pk_add_f32 v[70:71], v[70:71], v[180:181]
	v_pk_add_f32 v[64:65], v[64:65], v[182:183]
	v_pk_add_f32 v[66:67], v[66:67], v[184:185]
	global_store_dwordx4 v166, v[76:79], s[100:101]
	global_store_dwordx4 v167, v[72:75], s[100:101]
	global_store_dwordx4 v166, v[68:71], s[100:101] offset:512
	global_store_dwordx4 v167, v[64:67], s[100:101] offset:512
	v_cvt_pk_bf16_f32 v158, v76, v77
	v_cvt_pk_bf16_f32 v159, v78, v79
	v_cvt_pk_bf16_f32 v160, v72, v73
	v_cvt_pk_bf16_f32 v161, v74, v75
	v_cvt_pk_bf16_f32 v162, v68, v69
	v_cvt_pk_bf16_f32 v163, v70, v71
	v_cvt_pk_bf16_f32 v164, v64, v65
	v_cvt_pk_bf16_f32 v165, v66, v67
	global_store_dwordx2 v168, v[158:159], s[52:53]
	global_store_dwordx2 v169, v[160:161], s[52:53]
	global_store_dwordx2 v168, v[162:163], s[52:53] offset:256
	global_store_dwordx2 v169, v[164:165], s[52:53] offset:256
	v_mul_f32_e32 v148, v76, v76
	v_mul_f32_e32 v149, v72, v72
	v_fmac_f32_e32 v148, v77, v77
	v_fmac_f32_e32 v149, v73, v73
	v_fmac_f32_e32 v148, v78, v78
	v_fmac_f32_e32 v149, v74, v74
	v_fmac_f32_e32 v148, v79, v79
	v_fmac_f32_e32 v149, v75, v75
	v_fmac_f32_e32 v148, v68, v68
	v_fmac_f32_e32 v149, v64, v64
	v_fmac_f32_e32 v148, v69, v69
	v_fmac_f32_e32 v149, v65, v65
	v_fmac_f32_e32 v148, v70, v70
	v_fmac_f32_e32 v149, v66, v66
	v_fmac_f32_e32 v148, v71, v71
	v_fmac_f32_e32 v149, v67, v67
	s_nop 1
	v_add_f32_dpp v148, v148, v148 row_ror:8 row_mask:0xf bank_mask:0xf
	v_add_f32_dpp v149, v149, v149 row_ror:8 row_mask:0xf bank_mask:0xf
	v_mov_b32_e32 v134, v148
	v_mov_b32_e32 v147, v149
	s_nop 1
	v_permlane16_swap_b32_e32 v148, v134
	v_permlane16_swap_b32_e32 v149, v147
	v_add_f32_e32 v148, v148, v134
	v_add_f32_e32 v149, v149, v147
	v_mov_b32_e32 v134, v148
	v_mov_b32_e32 v147, v149
	s_nop 1
	v_permlane32_swap_b32_e32 v148, v134
	v_permlane32_swap_b32_e32 v149, v147
	v_add_f32_e32 v148, v148, v134
	v_add_f32_e32 v149, v149, v147
	v_cndmask_b32_e32 v148, v148, v149, vcc
	v_lshlrev_b32_e32 v134, 2, v150
	s_mov_b64 exec, s[4:5]
	global_atomic_add_f32 v134, v148, s[50:51] offset:192
	s_mov_b64 exec, -1
	s_branch .LBB0_1142

	.amdhsa_kernel _Z10fwd_kernel6Params
		.amdhsa_group_segment_fixed_size 0
		.amdhsa_private_segment_fixed_size 0
		.amdhsa_kernarg_size 424
		.amdhsa_user_sgpr_count 2
		.amdhsa_user_sgpr_dispatch_ptr 0
		.amdhsa_user_sgpr_queue_ptr 0
		.amdhsa_user_sgpr_kernarg_segment_ptr 1
		.amdhsa_user_sgpr_dispatch_id 0
		.amdhsa_user_sgpr_kernarg_preload_length 0
		.amdhsa_user_sgpr_kernarg_preload_offset 0
		.amdhsa_user_sgpr_private_segment_size 0
		.amdhsa_uses_dynamic_stack 0
		.amdhsa_enable_private_segment 0
		.amdhsa_system_sgpr_workgroup_id_x 1
		.amdhsa_system_sgpr_workgroup_id_y 0
		.amdhsa_system_sgpr_workgroup_id_z 0
		.amdhsa_system_sgpr_workgroup_info 0
		.amdhsa_system_vgpr_workitem_id 2
		.amdhsa_next_free_vgpr 248
		.amdhsa_next_free_sgpr 102
		.amdhsa_accum_offset 248
		.amdhsa_reserve_vcc 1
		.amdhsa_float_round_mode_32 0
		.amdhsa_float_round_mode_16_64 0
		.amdhsa_float_denorm_mode_32 3
		.amdhsa_float_denorm_mode_16_64 3
		.amdhsa_dx10_clamp 1
		.amdhsa_ieee_mode 1
		.amdhsa_fp16_overflow 0
		.amdhsa_tg_split 0
		.amdhsa_exception_fp_ieee_invalid_op 0
		.amdhsa_exception_fp_denorm_src 0
		.amdhsa_exception_fp_ieee_div_zero 0
		.amdhsa_exception_fp_ieee_overflow 0
		.amdhsa_exception_fp_ieee_underflow 0
		.amdhsa_exception_fp_ieee_inexact 0
		.amdhsa_exception_int_div_zero 0
	.end_amdhsa_kernel

amdhsa.kernels:
  - .agpr_count:     0
    .args:
      - .offset:         0
        .size:           168
        .value_kind:     by_value
      - .offset:         168
        .size:           4
        .value_kind:     hidden_block_count_x
      - .offset:         172
        .size:           4
        .value_kind:     hidden_block_count_y
      - .offset:         176
        .size:           4
        .value_kind:     hidden_block_count_z
      - .offset:         180
        .size:           2
        .value_kind:     hidden_group_size_x
      - .offset:         182
        .size:           2
        .value_kind:     hidden_group_size_y
      - .offset:         184
        .size:           2
        .value_kind:     hidden_group_size_z
      - .offset:         186
        .size:           2
        .value_kind:     hidden_remainder_x
      - .offset:         188
        .size:           2
        .value_kind:     hidden_remainder_y
      - .offset:         190
        .size:           2
        .value_kind:     hidden_remainder_z
      - .offset:         208
        .size:           8
        .value_kind:     hidden_global_offset_x
      - .offset:         216
        .size:           8
        .value_kind:     hidden_global_offset_y
      - .offset:         224
        .size:           8
        .value_kind:     hidden_global_offset_z
      - .offset:         232
        .size:           2
        .value_kind:     hidden_grid_dims
      - .offset:         256
        .size:           8
        .value_kind:     hidden_multigrid_sync_arg
      - .offset:         288
        .size:           4
        .value_kind:     hidden_dynamic_lds_size
    .group_segment_fixed_size: 0
    .kernarg_segment_align: 8
    .kernarg_segment_size: 424
    .language:       OpenCL C
    .language_version:
      - 2
      - 0
    .max_flat_workgroup_size: 512
    .name:           _Z10fwd_kernel6Params
    .private_segment_fixed_size: 0
    .sgpr_count:     108
    .sgpr_spill_count: 21
    .symbol:         _Z10fwd_kernel6Params.kd
    .uniform_work_group_size: 1
    .uses_dynamic_stack: false
    .vgpr_count:     248
    .vgpr_spill_count: 0
    .wavefront_size: 64
